# residual GEMM with 288 tiles: workgroups owning a quarter of a leftover tile run it before their 256x256 tile (staggers the HBM-bound epilogues of the two classes); next-unit stage prefetch added to t
# speedup vs baseline: 1.1207x; 1.0079x over previous
; #define PG8_WAIT_V(n) asm volatile("s_waitcnt vmcnt(" #n ")" ::: "memory")
;     __host__ __device__ bool next(int i, Unit& u) const {
;         const long L = (long)i * G + c; if (L >= nwg) return false;
;         int wgid = (int)L; { const int q = nwg / NXCD, r = nwg % NXCD, xcd = wgid % NXCD, off = wgid / NXCD; wgid = (xcd < r ? xcd * (q + 1) : r * (q + 1) + (xcd - r) * q) + off; }
;         const int nig = WGM * nN, gid = wgid / nig, fm = gid * WGM, gsz = (nM - fm) < WGM ? (nM - fm) : WGM;
;         u.pm = fm + ((wgid % nig) % gsz); u.pn = (wgid % nig) / gsz; return true;
; template <class Epi, class Sched, bool ALIGN_EPI = false, bool SP2 = false>
; __device__ __forceinline__ void gemm_phase(PG8_LAS unsigned char* lds, const Gemm g, const Sched& S, const Epi& E) {
;     ...
;     const int tid = tid_l, wid = __builtin_amdgcn_readfirstlane(tid >> 6), lane = tid & 63, wr = wid >> 2, wc = wid & 3, fr = lane & 15, fq = lane >> 4;
;     const int K = g.K, nt = K / BK;
;     unsigned voffA[2], voffB[2];
; #pragma unroll
;     for (int i = 0; i < 2; ++i) { int R, C; stage_rc(tid * 16 + i * 8192, R, C); const int Rb = Epi::PERM ? ((R & ~31) + perm32(R & 31)) : R;
;         voffA[i] = (unsigned)(R * K + C) * 2u; voffB[i] = (unsigned)(Rb * K + C) * 2u; }
;     const size_t kstep = (size_t)(BK * 2);
;     const size_t hstep = (size_t)HALF * K * 2;
;     const size_t tstep = 2 * hstep;
;     const unsigned ldsw = (unsigned)wid * 1024u;
;     const int aoff = lds_byte(wr * 64 + fr, fq * 8), boff = lds_byte(wc * 32 + fr, fq * 8);
;     ...
;     Unit cur, nxt; int ui = 0;
;     if (!S.next(0, cur)) return;
;     f32x4 acc[2][2][4][2];
; #pragma unroll
;     for (int a = 0; a < 2; ++a)
; #pragma unroll
;         for (int b = 0; b < 2; ++b)
; #pragma unroll
;             for (int m = 0; m < 4; ++m)
; #pragma unroll
;                 for (int n = 0; n < 2; ++n) acc[a][b][m][n] = (f32x4){0.f, 0.f, 0.f, 0.f};
;     bf16x8 At[4][2], B0[2][2], B1[2][2];
;     const char* cA = (const char*)g.A + (size_t)cur.pm * tstep; const char* cB = (const char*)g.Bt + (size_t)cur.pn * tstep;
;     S.a_ready(cur);
;     if constexpr (SP2) {
;         PG8_STAGE(PG8_SB(0, 0), cB, voffB); PG8_STAGE(PG8_SB(0, 1), cB + hstep, voffB); PG8_STAGE(PG8_SA(0, 0), cA, voffA); PG8_STAGE(PG8_SA(0, 1), cA + hstep, voffA);
;         if (wr == 1) PG8_BAR;
;         PG8_WAIT_V(2); PG8_BAR;
.LBB0_836:
	s_mov_b32 s1, 0x26000
	s_movk_i32 s96, 0x4000
	s_or_b64 exec, exec, s[10:11]
	v_mov_b32_e32 v0, v1
	s_waitcnt lgkmcnt(0)
	s_barrier
	v_mov_b32_e32 v20, v184
	v_readfirstlane_b32 s28, v0
	s_load_dwordx8 s[12:19], s[92:93], s28 offset:0x38
	s_load_dwordx4 s[20:23], s[92:93], s28 offset:0x80
	s_load_dwordx4 s[24:27], s[92:93], s28 offset:0xa0
	s_add_u32 s10, s92, s28
	s_addc_u32 s11, s93, 0
	s_lshr_b32 s64, s42, 6
	v_readfirstlane_b32 s28, v146
	s_cmp_ge_i32 s90, s64
	s_nop 0
	v_readfirstlane_b32 s44, v20
	s_cbranch_scc1 .LBB0_858
	v_lshlrev_b32_e32 v0, 4, v20
	v_add_u32_e32 v2, 0x2000, v0
	v_ashrrev_i32_e32 v3, 31, v2
	v_lshrrev_b32_e32 v3, 22, v3
	v_add_u32_e32 v3, v2, v3
	v_ashrrev_i32_e32 v3, 10, v3
	v_mul_i32_i24_e32 v4, 0x400, v3
	v_sub_u32_e32 v2, v2, v4
	v_lshrrev_b32_e32 v4, 4, v2
	v_bitop3_b32 v2, v4, v2, 32 bitop3:0x6c
	s_waitcnt lgkmcnt(0)
	s_add_u32 s85, s26, s8
	v_ashrrev_i32_e32 v4, 31, v2
	s_addc_u32 s86, s27, s9
	v_lshrrev_b32_e32 v4, 26, v4
	s_add_u32 s87, s26, s6
	v_add_u32_e32 v4, v2, v4
	s_addc_u32 s88, s27, s7
	s_lshr_b32 s91, s42, 9
	s_ashr_i32 s6, s44, 6
	v_ashrrev_i32_e32 v5, 6, v4
	v_and_b32_e32 v4, 0xc0, v4
	v_readlane_b32 s8, v254, 2
	s_load_dwordx2 s[30:31], s[10:11], 0x0
	s_load_dwordx2 s[40:41], s[10:11], 0x10
	s_lshr_b32 s89, s42, 8
	s_lshl_b32 s10, s3, 8
	s_lshl_b32 s90, s3, 9
	s_or_b32 s92, s91, 1
	s_ashr_i32 s7, s44, 8
	s_lshl_b32 s93, s6, 10
	v_sub_u32_e32 v2, v2, v4
	v_readlane_b32 s9, v254, 3
	v_ashrrev_i16_sdwa v2, v196, sext(v2) dst_sel:DWORD dst_unused:UNUSED_PAD src0_sel:DWORD src1_sel:BYTE_0
	s_and_b64 s[8:9], s[8:9], exec
	v_bfe_i32 v16, v2, 0, 16
	v_bfe_i32 v2, v20, 27, 1
	s_cselect_b32 s8, s92, s91
	v_readlane_b32 s9, v254, 4
	v_lshrrev_b32_e32 v2, 22, v2
	s_mul_i32 s8, s8, s9
	v_readlane_b32 s9, v254, 5
	v_add_u32_e32 v2, v0, v2
	s_add_i32 s8, s8, s9
	s_cmp_eq_u32 s64, 0x120
	s_cbranch_scc0 .Lsw_pdone
	s_cmp_eq_u32 s38, 0x100
	s_cbranch_scc0 .Lsw_pdone
	v_readlane_b32 s98, v254, 56
	s_nop 0
	s_cmp_lt_u32 s98, 0x80
	s_cbranch_scc0 .Lsw_pdone
	s_lshr_b32 s98, s98, 5
	s_lshl_b32 s99, s98, 2
	s_sub_i32 s8, s8, s99
	s_add_i32 s8, s8, 32
	s_add_i32 s98, s98, 1
	s_lshl_b32 s98, s98, 4
	s_or_b32 s101, s98, 0x80
.Lsw_pdone:
	v_and_b32_e32 v2, 0xfffffc00, v2
	s_ashr_i32 s9, s8, 31
	v_sub_u32_e32 v0, v0, v2
	s_lshr_b32 s9, s9, 28
	v_lshlrev_b32_e32 v6, 3, v3
	v_lshrrev_b32_e32 v2, 4, v0
	s_add_i32 s9, s8, s9
	v_writelane_b32 v255, s28, 10
	v_and_b32_e32 v6, 0x7ffffff0, v6
	v_bitop3_b32 v0, v2, v0, 32 bitop3:0x6c
	s_ashr_i32 s28, s9, 4
	v_add_u32_e32 v5, v5, v6
	v_lshlrev_b32_e32 v3, 5, v3
	v_ashrrev_i32_e32 v2, 31, v0
	s_lshl_b32 s28, s28, 2
	v_mul_lo_u32 v14, v5, s3
	v_and_b32_e32 v15, 32, v3
	v_lshrrev_b32_e32 v2, 26, v2
	s_sub_i32 s29, s89, s28
	v_or_b32_e32 v3, v14, v15
	v_add_u32_e32 v2, v0, v2
	s_min_i32 s29, s29, 4
	v_add_lshl_u32 v130, v3, v16, 1
	v_ashrrev_i32_e32 v3, 6, v2
	v_and_b32_e32 v2, 0xc0, v2
	s_abs_i32 s35, s29
	v_sub_u32_e32 v0, v0, v2
	v_cvt_f32_u32_e32 v2, s35
	s_sub_i32 s42, 0, s35
	s_and_b32 s9, s9, -16
	s_sub_i32 s8, s8, s9
	v_rcp_iflag_f32_e32 v2, v2
	s_abs_i32 s34, s8
	s_xor_b32 s9, s8, s29
	s_ashr_i32 s9, s9, 31
	v_mul_f32_e32 v2, 0x4f7ffffe, v2
	v_cvt_u32_f32_e32 v2, v2
	v_ashrrev_i32_e32 v4, 31, v20
	v_lshrrev_b32_e32 v4, 26, v4
	v_add_u32_e32 v4, v20, v4
	v_readfirstlane_b32 s43, v2
	s_mul_i32 s42, s42, s43
	s_mul_hi_u32 s42, s43, s42
	s_add_i32 s43, s43, s42
	s_mul_hi_u32 s42, s34, s43
	s_mul_i32 s43, s42, s35
	s_sub_i32 s34, s34, s43
	s_add_i32 s43, s42, 1
	s_sub_i32 s45, s34, s35
	s_cmp_ge_u32 s34, s35
	s_cselect_b32 s42, s43, s42
	s_cselect_b32 s34, s45, s34
	s_add_i32 s43, s42, 1
	s_cmp_ge_u32 s34, s35
	s_cselect_b32 s34, s43, s42
	v_ashrrev_i32_e32 v4, 6, v4
	s_xor_b32 s34, s34, s9
	v_lshlrev_b32_e32 v5, 3, v4
	s_sub_i32 s62, s34, s9
	v_and_b32_e32 v5, 0x7ffffff0, v5
	s_mul_i32 s9, s62, s29
	v_add_u32_e32 v3, v3, v5
	s_sub_i32 s8, s8, s9
	v_mul_lo_u32 v17, v3, s3
	v_lshlrev_b32_e32 v3, 5, v4
	s_add_i32 s52, s28, s8
	s_mul_i32 s9, s90, s62
	v_and_b32_e32 v18, 32, v3
	v_ashrrev_i16_sdwa v0, v196, sext(v0) dst_sel:DWORD dst_unused:UNUSED_PAD src0_sel:DWORD src1_sel:BYTE_0
	s_mul_hi_i32 s8, s90, s62
	s_add_u32 s76, s87, s9
	v_or_b32_e32 v3, v17, v18
	v_bfe_i32 v19, v0, 0, 16
	s_addc_u32 s77, s88, s8
	s_add_i32 s94, s93, 0
	v_add_lshl_u32 v0, v3, v19, 1
	s_add_i32 m0, s94, 0x10000
	s_mul_i32 s29, s90, s52
	global_load_lds_dwordx4 v0, s[76:77]
	s_add_i32 m0, s94, 0x12000
	s_add_u32 s8, s76, s10
	global_load_lds_dwordx4 v130, s[76:77]
	s_addc_u32 s9, s77, 0
	s_add_i32 m0, s94, 0x14000
	s_mul_hi_i32 s28, s90, s52
	global_load_lds_dwordx4 v0, s[8:9]
	s_add_i32 m0, s94, 0x16000
	s_add_u32 s48, s85, s29
	v_mov_b32_e32 v131, v1
	s_addc_u32 s49, s86, s28
	s_add_i32 s95, s94, 0x2000
	v_lshl_add_u64 v[6:7], s[8:9], 0, v[0:1]
	v_lshl_add_u64 v[8:9], s[8:9], 0, v[130:131]
	global_load_lds_dwordx4 v130, s[8:9]
	s_mov_b32 m0, s94
	s_add_u32 s8, s48, s10
	global_load_lds_dwordx4 v0, s[48:49]
	s_mov_b32 m0, s95
	s_addc_u32 s9, s49, 0
	s_add_i32 s84, s94, 0x4000
	global_load_lds_dwordx4 v130, s[48:49]
	s_mov_b32 m0, s84
	s_add_i32 s74, s94, 0x6000
	global_load_lds_dwordx4 v0, s[8:9]
	s_mov_b32 m0, s74
	s_cmp_eq_u32 s7, 1
	global_load_lds_dwordx4 v130, s[8:9]
	s_mov_b32 s11, s65
	v_lshl_add_u64 v[2:3], s[76:77], 0, v[0:1]
	v_lshl_add_u64 v[4:5], s[76:77], 0, v[130:131]
	v_lshl_add_u64 v[10:11], s[48:49], 0, v[0:1]
	v_lshl_add_u64 v[12:13], s[48:49], 0, v[130:131]
	s_cselect_b64 s[28:29], -1, 0
	s_cmp_lg_u32 s7, 1
	s_cbranch_scc1 .LBB0_839
	s_barrier

;     __host__ __device__ bool next(int i, Unit& u) const {
;         const long L = (long)i * G + c; if (L >= nwg) return false;
;         int wgid = (int)L; { const int q = nwg / NXCD, r = nwg % NXCD, xcd = wgid % NXCD, off = wgid / NXCD; wgid = (xcd < r ? xcd * (q + 1) : r * (q + 1) + (xcd - r) * q) + off; }
;         const int nig = WGM * nN, gid = wgid / nig, fm = gid * WGM, gsz = (nM - fm) < WGM ? (nM - fm) : WGM;
;         u.pm = fm + ((wgid % nig) % gsz); u.pn = (wgid % nig) / gsz; return true;
.LBB0_842:
	s_lshr_b32 s101, s101, 4
	s_add_i32 s11, s11, 1
	s_mul_i32 s6, s11, s39
	s_mul_hi_u32 s7, s11, s38
	s_add_i32 s7, s7, s6
	s_mul_i32 s6, s11, s38
	v_readlane_b32 s8, v254, 56
	v_readlane_b32 s9, v254, 57
	s_add_u32 s6, s6, s8
	s_addc_u32 s7, s7, s9
	s_bitcmp1_b32 s101, 3
	s_cbranch_scc0 .Lsw_hdone
	s_sub_u32 s6, s6, s38
	s_subb_u32 s7, s7, 0
.Lsw_hdone:
	s_sub_i32 s80, s6, s8
	s_sub_i32 s81, s64, s80
	s_cmp_lt_i32 s81, 1
	s_cbranch_scc1 .Lhq_done
	s_lshl_b32 s82, s81, 2
	s_cmp_gt_u32 s82, s38
	s_cbranch_scc1 .Lhq_done
	s_cmp_ge_u32 s8, s82
	s_cbranch_scc1 .Lhq_done
	s_and_b32 s101, s101, 7
	s_or_b32 s101, s101, 16
	s_mov_b32 s80, s8
	s_cmp_lt_u32 s80, s81
	s_cbranch_scc1 .Lhq_done
	s_sub_u32 s80, s80, s81
	s_and_b32 s101, s101, 7
	s_or_b32 s101, s101, 32
	s_cmp_lt_u32 s80, s81
	s_cbranch_scc1 .Lhq_adj
	s_sub_u32 s80, s80, s81
	s_and_b32 s101, s101, 7
	s_or_b32 s101, s101, 48
	s_cmp_lt_u32 s80, s81
	s_cbranch_scc1 .Lhq_adj
	s_sub_u32 s80, s80, s81
	s_and_b32 s101, s101, 7
	s_or_b32 s101, s101, 64

; #define PG8_STAGE(bufoff, gbase, voff) do { _Pragma("unroll") for (int _i = 0; _i < 2; ++_i) \
;         __builtin_amdgcn_global_load_lds((const unsigned*)((const char*)(gbase) + (voff)[_i]), (PG8_LAS unsigned*)(lds + (bufoff) + ldsw + _i * 8192), 16, 0, 0); } while (0)
; #define PG8_LDA(dst, b, h) do { _Pragma("unroll") for (int m = 0; m < 4; ++m) _Pragma("unroll") for (int k = 0; k < 2; ++k) dst[m][k] = *(const PG8_LAS bf16x8*)(lds + PG8_SA(b, h) + aoff + m * 2048 + k * 1024); } while (0)
; #define PG8_LDB(dst, b, h) do { _Pragma("unroll") for (int n = 0; n < 2; ++n) _Pragma("unroll") for (int k = 0; k < 2; ++k) dst[n][k] = *(const PG8_LAS bf16x8*)(lds + PG8_SB(b, h) + boff + n * 2048 + k * 1024); } while (0)
; template <class Epi, class Sched, bool ALIGN_EPI = false, bool SP2 = false>
; __device__ __forceinline__ void gemm_phase(PG8_LAS unsigned char* lds, const Gemm g, const Sched& S, const Epi& E) {
;     ...
;         for (int t = 0; t < nt; t += 2) {
;             const bool last = (t == nt - 2);
;             const char* a1 = cA + (size_t)(t + 1) * kstep;
;             const char* a2 = last ? nA : cA + (size_t)(t + 2) * kstep; const char* b2 = last ? nB : cB + (size_t)(t + 2) * kstep;
;             const char* a3 = a2 + kstep; const char* b3 = b2 + kstep;
;             if (last && has_next) S.a_ready(nxt);
;             if constexpr (SP2) {
;             PG8_LDB(B0, 0, 0); PG8_LDB(B1, 0, 1); PG8_SCHED; PG8_LDA(At, 0, 0); PG8_STAGE(PG8_SA(1, 1), a1 + hstep, voffA);
;             PG8_WAIT_V(8); PG8_WAIT_L(0); PG8_BAR; PG8_MMA(0, 0, At, B0); PG8_MMA(0, 1, At, B1); PG8_BAR; PG8_SCHED;
;             PG8_LDA(At, 0, 1); PG8_STAGE(PG8_SB(0, 0), b2, voffB); PG8_STAGE(PG8_SB(0, 1), b2 + hstep, voffB); PG8_STAGE(PG8_SA(0, 0), a2, voffA);
;             PG8_WAIT_V(8); PG8_WAIT_L(0); PG8_BAR; PG8_MMA(1, 0, At, B0); PG8_MMA(1, 1, At, B1); PG8_BAR; PG8_SCHED;
;             PG8_LDB(B0, 1, 0); PG8_LDB(B1, 1, 1); PG8_SCHED; PG8_LDA(At, 1, 0); PG8_STAGE(PG8_SA(0, 1), a2 + hstep, voffA);
;             PG8_WAIT_V(8); PG8_WAIT_L(0); PG8_BAR; PG8_MMA(0, 0, At, B0); PG8_MMA(0, 1, At, B1); PG8_BAR; PG8_SCHED;
;             PG8_LDA(At, 1, 1); PG8_STAGE(PG8_SB(1, 0), b3, voffB); PG8_STAGE(PG8_SB(1, 1), b3 + hstep, voffB); PG8_STAGE(PG8_SA(1, 0), a3, voffA);
;             PG8_WAIT_V(8); PG8_WAIT_L(0); PG8_BAR; PG8_MMA(1, 0, At, B0); PG8_MMA(1, 1, At, B1); PG8_BAR; PG8_SCHED;
.Lkq_1_loop:
	v_add_u32_e32 v136, 0x10000, v147
	ds_read_b128 v[148:151], v136
	ds_read_b128 v[152:155], v136 offset:1024
	ds_read_b128 v[156:159], v136 offset:2048
	ds_read_b128 v[160:163], v136 offset:3072
	ds_read_b128 v[202:205], v165
	ds_read_b128 v[208:211], v165 offset:1024
	ds_read_b128 v[212:215], v165 offset:2048
	ds_read_b128 v[216:219], v165 offset:3072
	ds_read_b128 v[220:223], v165 offset:4096
	ds_read_b128 v[224:227], v165 offset:5120
	ds_read_b128 v[228:231], v165 offset:6144
	ds_read_b128 v[232:235], v165 offset:7168
	v_lshl_add_u64 v[136:137], s[76:77], 0, v[0:1]
	s_add_i32 m0, s94, 0xc000
	v_lshl_add_u64 v[144:145], s[76:77], 0, v[130:131]
	global_load_lds_dwordx4 v[136:137], off
	s_add_i32 m0, s94, 0xe000
	s_nop 0
	global_load_lds_dwordx4 v[144:145], off
	v_lshl_add_u64 v[182:183], vcc, 0, v[0:1]
	s_add_i32 m0, s93, 0x1c000
	v_lshl_add_u64 v[236:237], vcc, 0, v[130:131]
	global_load_lds_dwordx4 v[182:183], off
	s_add_i32 m0, s93, 0x1e000
	s_nop 0
	global_load_lds_dwordx4 v[236:237], off
	s_cmp_lt_u32 s82, s59
	s_cselect_b32 s83, 0x80, 0
	s_add_u32 s76, s76, s83
	s_addc_u32 s77, s77, 0
	s_add_u32 vcc_lo, vcc_lo, s83
	s_addc_u32 vcc_hi, vcc_hi, 0
	s_add_i32 s82, s82, 1
	s_waitcnt vmcnt(8)
	s_waitcnt lgkmcnt(0)
	s_barrier
	s_setprio 1
	v_mfma_f32_16x16x32_bf16 v[126:129], v[148:151], v[202:205], v[126:129]
	v_mfma_f32_16x16x32_bf16 v[122:125], v[156:159], v[202:205], v[122:125]
	v_mfma_f32_16x16x32_bf16 v[110:113], v[148:151], v[212:215], v[110:113]
	v_mfma_f32_16x16x32_bf16 v[106:109], v[156:159], v[212:215], v[106:109]
	v_mfma_f32_16x16x32_bf16 v[94:97], v[148:151], v[220:223], v[94:97]
	v_mfma_f32_16x16x32_bf16 v[90:93], v[156:159], v[220:223], v[90:93]
	v_mfma_f32_16x16x32_bf16 v[78:81], v[148:151], v[228:231], v[78:81]
	v_mfma_f32_16x16x32_bf16 v[74:77], v[156:159], v[228:231], v[74:77]
	v_mfma_f32_16x16x32_bf16 v[126:129], v[152:155], v[208:211], v[126:129]
	v_mfma_f32_16x16x32_bf16 v[122:125], v[160:163], v[208:211], v[122:125]
	v_mfma_f32_16x16x32_bf16 v[110:113], v[152:155], v[216:219], v[110:113]
	v_mfma_f32_16x16x32_bf16 v[106:109], v[160:163], v[216:219], v[106:109]
	v_mfma_f32_16x16x32_bf16 v[94:97], v[152:155], v[224:227], v[94:97]
	v_mfma_f32_16x16x32_bf16 v[90:93], v[160:163], v[224:227], v[90:93]
	v_mfma_f32_16x16x32_bf16 v[78:81], v[152:155], v[232:235], v[78:81]
	v_mfma_f32_16x16x32_bf16 v[74:77], v[160:163], v[232:235], v[74:77]
	s_setprio 0
	s_barrier
	v_add_u32_e32 v136, 0x18000, v147
	ds_read_b128 v[148:151], v136
	ds_read_b128 v[152:155], v136 offset:1024
	ds_read_b128 v[156:159], v136 offset:2048
	ds_read_b128 v[160:163], v136 offset:3072
	ds_read_b128 v[202:205], v165 offset:32768
	ds_read_b128 v[208:211], v165 offset:33792
	ds_read_b128 v[212:215], v165 offset:34816
	ds_read_b128 v[216:219], v165 offset:35840
	ds_read_b128 v[220:223], v165 offset:36864
	ds_read_b128 v[224:227], v165 offset:37888
	ds_read_b128 v[228:231], v165 offset:38912
	ds_read_b128 v[232:235], v165 offset:39936
	v_lshl_add_u64 v[136:137], s[76:77], 0, v[0:1]
	s_add_i32 m0, s94, 0x0
	v_lshl_add_u64 v[144:145], s[76:77], 0, v[130:131]
	global_load_lds_dwordx4 v[136:137], off
	s_add_i32 m0, s94, 0x2000
	s_nop 0
	global_load_lds_dwordx4 v[144:145], off
	v_lshl_add_u64 v[182:183], vcc, 0, v[0:1]
	s_add_i32 m0, s93, 0x10000
	v_lshl_add_u64 v[236:237], vcc, 0, v[130:131]
	global_load_lds_dwordx4 v[182:183], off
	s_add_i32 m0, s93, 0x12000
	s_nop 0
	global_load_lds_dwordx4 v[236:237], off
	s_cmp_lt_u32 s82, s59
	s_cselect_b32 s83, 0x80, 0
	s_add_u32 s76, s76, s83
	s_addc_u32 s77, s77, 0
	s_add_u32 vcc_lo, vcc_lo, s83
	s_addc_u32 vcc_hi, vcc_hi, 0
	s_add_i32 s82, s82, 1
	s_waitcnt vmcnt(8)
	s_waitcnt lgkmcnt(0)
	s_barrier
	s_setprio 1
	v_mfma_f32_16x16x32_bf16 v[126:129], v[148:151], v[202:205], v[126:129]
	v_mfma_f32_16x16x32_bf16 v[122:125], v[156:159], v[202:205], v[122:125]
	v_mfma_f32_16x16x32_bf16 v[110:113], v[148:151], v[212:215], v[110:113]
	v_mfma_f32_16x16x32_bf16 v[106:109], v[156:159], v[212:215], v[106:109]
	v_mfma_f32_16x16x32_bf16 v[94:97], v[148:151], v[220:223], v[94:97]
	v_mfma_f32_16x16x32_bf16 v[90:93], v[156:159], v[220:223], v[90:93]
	v_mfma_f32_16x16x32_bf16 v[78:81], v[148:151], v[228:231], v[78:81]
	v_mfma_f32_16x16x32_bf16 v[74:77], v[156:159], v[228:231], v[74:77]
	v_mfma_f32_16x16x32_bf16 v[126:129], v[152:155], v[208:211], v[126:129]
	v_mfma_f32_16x16x32_bf16 v[122:125], v[160:163], v[208:211], v[122:125]
	v_mfma_f32_16x16x32_bf16 v[110:113], v[152:155], v[216:219], v[110:113]
	v_mfma_f32_16x16x32_bf16 v[106:109], v[160:163], v[216:219], v[106:109]
	v_mfma_f32_16x16x32_bf16 v[94:97], v[152:155], v[224:227], v[94:97]
	v_mfma_f32_16x16x32_bf16 v[90:93], v[160:163], v[224:227], v[90:93]
	v_mfma_f32_16x16x32_bf16 v[78:81], v[152:155], v[232:235], v[78:81]
	v_mfma_f32_16x16x32_bf16 v[74:77], v[160:163], v[232:235], v[74:77]
	s_setprio 0
	s_barrier
	v_add_u32_e32 v136, 0x14000, v147
	ds_read_b128 v[148:151], v136
	ds_read_b128 v[152:155], v136 offset:1024
	ds_read_b128 v[156:159], v136 offset:2048
	ds_read_b128 v[160:163], v136 offset:3072
	ds_read_b128 v[202:205], v165 offset:16384
	ds_read_b128 v[208:211], v165 offset:17408
	ds_read_b128 v[212:215], v165 offset:18432
	ds_read_b128 v[216:219], v165 offset:19456
	ds_read_b128 v[220:223], v165 offset:20480
	ds_read_b128 v[224:227], v165 offset:21504
	ds_read_b128 v[228:231], v165 offset:22528
	ds_read_b128 v[232:235], v165 offset:23552
	v_lshl_add_u64 v[136:137], s[76:77], 0, v[0:1]
	s_add_i32 m0, s94, 0x8000
	v_lshl_add_u64 v[144:145], s[76:77], 0, v[130:131]
	global_load_lds_dwordx4 v[136:137], off
	s_add_i32 m0, s94, 0xa000
	s_nop 0
	global_load_lds_dwordx4 v[144:145], off
	v_lshl_add_u64 v[182:183], vcc, 0, v[0:1]
	s_add_i32 m0, s93, 0x18000
	v_lshl_add_u64 v[236:237], vcc, 0, v[130:131]
	global_load_lds_dwordx4 v[182:183], off
	s_add_i32 m0, s93, 0x1a000
	s_nop 0
	global_load_lds_dwordx4 v[236:237], off
	s_cmp_lt_u32 s82, s59
	s_cselect_b32 s83, 0x80, 0
	s_add_u32 s76, s76, s83
	s_addc_u32 s77, s77, 0
	s_add_u32 vcc_lo, vcc_lo, s83
	s_addc_u32 vcc_hi, vcc_hi, 0
	s_add_i32 s82, s82, 1
	s_waitcnt vmcnt(8)
	s_waitcnt lgkmcnt(0)
	s_barrier
; #define PG8_STAGE(bufoff, gbase, voff) do { _Pragma("unroll") for (int _i = 0; _i < 2; ++_i) \
;         __builtin_amdgcn_global_load_lds((const unsigned*)((const char*)(gbase) + (voff)[_i]), (PG8_LAS unsigned*)(lds + (bufoff) + ldsw + _i * 8192), 16, 0, 0); } while (0)
; #define PG8_BAR __builtin_amdgcn_s_barrier()
; template <class Epi, class Sched, bool ALIGN_EPI = false, bool SP2 = false>
; __device__ __forceinline__ void gemm_phase(PG8_LAS unsigned char* lds, const Gemm g, const Sched& S, const Epi& E) {
;     ...
;         PG8_STAGE(PG8_SB(0, 0), cB, voffB); PG8_STAGE(PG8_SB(0, 1), cB + hstep, voffB); PG8_STAGE(PG8_SA(0, 0), cA, voffA); PG8_STAGE(PG8_SA(0, 1), cA + hstep, voffA);
;         if (wr == 1) PG8_BAR;
;         PG8_WAIT_V(2); PG8_BAR;
;         PG8_STAGE(PG8_SB(1, 0), cB + kstep, voffB); PG8_STAGE(PG8_SA(1, 0), cA + kstep, voffA); PG8_STAGE(PG8_SB(1, 1), cB + hstep + kstep, voffB);
;     ...
;         for (int t = 0; t < nt; t += 2) {
;             const bool last = (t == nt - 2);
;             const char* a1 = cA + (size_t)(t + 1) * kstep;
;             const char* a2 = last ? nA : cA + (size_t)(t + 2) * kstep; const char* b2 = last ? nB : cB + (size_t)(t + 2) * kstep;
;             const char* a3 = a2 + kstep; const char* b3 = b2 + kstep;
;             if (last && has_next) S.a_ready(nxt);
;             if constexpr (SP2) {
;             PG8_LDB(B0, 0, 0); PG8_LDB(B1, 0, 1); PG8_SCHED; PG8_LDA(At, 0, 0); PG8_STAGE(PG8_SA(1, 1), a1 + hstep, voffA);
;             PG8_WAIT_V(8); PG8_WAIT_L(0); PG8_BAR; PG8_MMA(0, 0, At, B0); PG8_MMA(0, 1, At, B1); PG8_BAR; PG8_SCHED;
;             PG8_LDA(At, 0, 1); PG8_STAGE(PG8_SB(0, 0), b2, voffB); PG8_STAGE(PG8_SB(0, 1), b2 + hstep, voffB); PG8_STAGE(PG8_SA(0, 0), a2, voffA);
;             PG8_WAIT_V(8); PG8_WAIT_L(0); PG8_BAR; PG8_MMA(1, 0, At, B0); PG8_MMA(1, 1, At, B1); PG8_BAR; PG8_SCHED;
;             PG8_LDB(B0, 1, 0); PG8_LDB(B1, 1, 1); PG8_SCHED; PG8_LDA(At, 1, 0); PG8_STAGE(PG8_SA(0, 1), a2 + hstep, voffA);
;             PG8_WAIT_V(8); PG8_WAIT_L(0); PG8_BAR; PG8_MMA(0, 0, At, B0); PG8_MMA(0, 1, At, B1); PG8_BAR; PG8_SCHED;
;             PG8_LDA(At, 1, 1); PG8_STAGE(PG8_SB(1, 0), b3, voffB); PG8_STAGE(PG8_SB(1, 1), b3 + hstep, voffB); PG8_STAGE(PG8_SA(1, 0), a3, voffA);
;             PG8_WAIT_V(8); PG8_WAIT_L(0); PG8_BAR; PG8_MMA(1, 0, At, B0); PG8_MMA(1, 1, At, B1); PG8_BAR; PG8_SCHED;
	s_setprio 1
	v_mfma_f32_16x16x32_bf16 v[126:129], v[148:151], v[202:205], v[126:129]
	v_mfma_f32_16x16x32_bf16 v[122:125], v[156:159], v[202:205], v[122:125]
	v_mfma_f32_16x16x32_bf16 v[110:113], v[148:151], v[212:215], v[110:113]
	v_mfma_f32_16x16x32_bf16 v[106:109], v[156:159], v[212:215], v[106:109]
	v_mfma_f32_16x16x32_bf16 v[94:97], v[148:151], v[220:223], v[94:97]
	v_mfma_f32_16x16x32_bf16 v[90:93], v[156:159], v[220:223], v[90:93]
	v_mfma_f32_16x16x32_bf16 v[78:81], v[148:151], v[228:231], v[78:81]
	v_mfma_f32_16x16x32_bf16 v[74:77], v[156:159], v[228:231], v[74:77]
	v_mfma_f32_16x16x32_bf16 v[126:129], v[152:155], v[208:211], v[126:129]
	v_mfma_f32_16x16x32_bf16 v[122:125], v[160:163], v[208:211], v[122:125]
	v_mfma_f32_16x16x32_bf16 v[110:113], v[152:155], v[216:219], v[110:113]
	v_mfma_f32_16x16x32_bf16 v[106:109], v[160:163], v[216:219], v[106:109]
	v_mfma_f32_16x16x32_bf16 v[94:97], v[152:155], v[224:227], v[94:97]
	v_mfma_f32_16x16x32_bf16 v[90:93], v[160:163], v[224:227], v[90:93]
	v_mfma_f32_16x16x32_bf16 v[78:81], v[152:155], v[232:235], v[78:81]
	v_mfma_f32_16x16x32_bf16 v[74:77], v[160:163], v[232:235], v[74:77]
	s_setprio 0
	s_barrier
	v_add_u32_e32 v136, 0x1c000, v147
	ds_read_b128 v[148:151], v136
	ds_read_b128 v[152:155], v136 offset:1024
	ds_read_b128 v[156:159], v136 offset:2048
	ds_read_b128 v[160:163], v136 offset:3072
	ds_read_b128 v[202:205], v165 offset:49152
	ds_read_b128 v[208:211], v165 offset:50176
	ds_read_b128 v[212:215], v165 offset:51200
	ds_read_b128 v[216:219], v165 offset:52224
	ds_read_b128 v[220:223], v165 offset:53248
	ds_read_b128 v[224:227], v165 offset:54272
	ds_read_b128 v[228:231], v165 offset:55296
	ds_read_b128 v[232:235], v165 offset:56320
	v_lshl_add_u64 v[136:137], s[76:77], 0, v[0:1]
	s_add_i32 m0, s94, 0x4000
	v_lshl_add_u64 v[144:145], s[76:77], 0, v[130:131]
	global_load_lds_dwordx4 v[136:137], off
	s_add_i32 m0, s94, 0x6000
	s_nop 0
	global_load_lds_dwordx4 v[144:145], off
	v_lshl_add_u64 v[182:183], vcc, 0, v[0:1]
	s_add_i32 m0, s93, 0x14000
	v_lshl_add_u64 v[236:237], vcc, 0, v[130:131]
	global_load_lds_dwordx4 v[182:183], off
	s_add_i32 m0, s93, 0x16000
	s_nop 0
	global_load_lds_dwordx4 v[236:237], off
	s_cmp_lt_u32 s82, s59
	s_cselect_b32 s83, 0x80, 0
	s_add_u32 s76, s76, s83
	s_addc_u32 s77, s77, 0
	s_add_u32 vcc_lo, vcc_lo, s83
	s_addc_u32 vcc_hi, vcc_hi, 0
	s_add_i32 s82, s82, 1
	s_waitcnt vmcnt(8)
	s_waitcnt lgkmcnt(0)
	s_barrier
	s_setprio 1
	v_mfma_f32_16x16x32_bf16 v[126:129], v[148:151], v[202:205], v[126:129]
	v_mfma_f32_16x16x32_bf16 v[122:125], v[156:159], v[202:205], v[122:125]
	v_mfma_f32_16x16x32_bf16 v[110:113], v[148:151], v[212:215], v[110:113]
	v_mfma_f32_16x16x32_bf16 v[106:109], v[156:159], v[212:215], v[106:109]
	v_mfma_f32_16x16x32_bf16 v[94:97], v[148:151], v[220:223], v[94:97]
	v_mfma_f32_16x16x32_bf16 v[90:93], v[156:159], v[220:223], v[90:93]
	v_mfma_f32_16x16x32_bf16 v[78:81], v[148:151], v[228:231], v[78:81]
	v_mfma_f32_16x16x32_bf16 v[74:77], v[156:159], v[228:231], v[74:77]
	v_mfma_f32_16x16x32_bf16 v[126:129], v[152:155], v[208:211], v[126:129]
	v_mfma_f32_16x16x32_bf16 v[122:125], v[160:163], v[208:211], v[122:125]
	v_mfma_f32_16x16x32_bf16 v[110:113], v[152:155], v[216:219], v[110:113]
	v_mfma_f32_16x16x32_bf16 v[106:109], v[160:163], v[216:219], v[106:109]
	v_mfma_f32_16x16x32_bf16 v[94:97], v[152:155], v[224:227], v[94:97]
	v_mfma_f32_16x16x32_bf16 v[90:93], v[160:163], v[224:227], v[90:93]
	v_mfma_f32_16x16x32_bf16 v[78:81], v[152:155], v[232:235], v[78:81]
	v_mfma_f32_16x16x32_bf16 v[74:77], v[160:163], v[232:235], v[74:77]
	s_setprio 0
	s_barrier
	s_add_i32 s83, s82, -3
	s_cmp_lt_u32 s83, s79
	s_cbranch_scc1 .Lkq_1_loop
	s_mov_b64 s[76:77], s[8:9]
	s_mov_b64 vcc, s[46:47]
	v_lshl_add_u64 v[136:137], vcc, 0, v[0:1]
	s_add_i32 m0, s93, 0x10000
	v_lshl_add_u64 v[144:145], vcc, 0, v[130:131]
	global_load_lds_dwordx4 v[136:137], off
	s_add_i32 m0, s93, 0x12000
	s_nop 0
	global_load_lds_dwordx4 v[144:145], off
	s_add_u32 vcc_lo, vcc_lo, s10
	s_addc_u32 vcc_hi, vcc_hi, 0
	v_lshl_add_u64 v[136:137], vcc, 0, v[0:1]
	s_add_i32 m0, s93, 0x14000
	v_lshl_add_u64 v[144:145], vcc, 0, v[130:131]
	global_load_lds_dwordx4 v[136:137], off
	s_add_i32 m0, s93, 0x16000
	s_nop 0
	global_load_lds_dwordx4 v[144:145], off
	v_lshl_add_u64 v[136:137], s[76:77], 0, v[0:1]
	s_add_i32 m0, s94, 0x0
	v_lshl_add_u64 v[144:145], s[76:77], 0, v[130:131]
	global_load_lds_dwordx4 v[136:137], off
	s_add_i32 m0, s94, 0x2000
	s_nop 0
	global_load_lds_dwordx4 v[144:145], off
	s_add_u32 s76, s76, s10
	s_addc_u32 s77, s77, 0
	v_lshl_add_u64 v[136:137], s[76:77], 0, v[0:1]
	s_add_i32 m0, s94, 0x4000
	v_lshl_add_u64 v[144:145], s[76:77], 0, v[130:131]
	global_load_lds_dwordx4 v[136:137], off
	s_add_i32 m0, s94, 0x6000
	s_nop 0
	global_load_lds_dwordx4 v[144:145], off
	s_add_u32 s76, s8, 0x80
	s_addc_u32 s77, s9, 0
	s_add_u32 vcc_lo, s46, 0x80
	s_addc_u32 vcc_hi, s47, 0
	v_lshl_add_u64 v[136:137], vcc, 0, v[0:1]
	s_add_i32 m0, s93, 0x18000
	v_lshl_add_u64 v[144:145], vcc, 0, v[130:131]
	global_load_lds_dwordx4 v[136:137], off
	s_add_i32 m0, s93, 0x1a000
	s_nop 0
	global_load_lds_dwordx4 v[144:145], off
	s_add_u32 vcc_lo, vcc_lo, s10
	s_addc_u32 vcc_hi, vcc_hi, 0
	v_lshl_add_u64 v[136:137], vcc, 0, v[0:1]
	s_add_i32 m0, s93, 0x1c000
	v_lshl_add_u64 v[144:145], vcc, 0, v[130:131]
	global_load_lds_dwordx4 v[136:137], off
	s_add_i32 m0, s93, 0x1e000
	s_nop 0
	global_load_lds_dwordx4 v[144:145], off
	v_lshl_add_u64 v[136:137], s[76:77], 0, v[0:1]
	s_add_i32 m0, s94, 0x8000
	v_lshl_add_u64 v[144:145], s[76:77], 0, v[130:131]
	global_load_lds_dwordx4 v[136:137], off
	s_add_i32 m0, s94, 0xa000
	s_nop 0
	global_load_lds_dwordx4 v[144:145], off
	s_branch .Lkq_exit

; #define PG8_STAGE(bufoff, gbase, voff) do { _Pragma("unroll") for (int _i = 0; _i < 2; ++_i) \
;         __builtin_amdgcn_global_load_lds((const unsigned*)((const char*)(gbase) + (voff)[_i]), (PG8_LAS unsigned*)(lds + (bufoff) + ldsw + _i * 8192), 16, 0, 0); } while (0)
; #define PG8_LDA(dst, b, h) do { _Pragma("unroll") for (int m = 0; m < 4; ++m) _Pragma("unroll") for (int k = 0; k < 2; ++k) dst[m][k] = *(const PG8_LAS bf16x8*)(lds + PG8_SA(b, h) + aoff + m * 2048 + k * 1024); } while (0)
; #define PG8_LDB(dst, b, h) do { _Pragma("unroll") for (int n = 0; n < 2; ++n) _Pragma("unroll") for (int k = 0; k < 2; ++k) dst[n][k] = *(const PG8_LAS bf16x8*)(lds + PG8_SB(b, h) + boff + n * 2048 + k * 1024); } while (0)
; template <class Epi, class Sched, bool ALIGN_EPI = false, bool SP2 = false>
; __device__ __forceinline__ void gemm_phase(PG8_LAS unsigned char* lds, const Gemm g, const Sched& S, const Epi& E) {
;     ...
;         for (int t = 0; t < nt; t += 2) {
;             const bool last = (t == nt - 2);
;             const char* a1 = cA + (size_t)(t + 1) * kstep;
;             const char* a2 = last ? nA : cA + (size_t)(t + 2) * kstep; const char* b2 = last ? nB : cB + (size_t)(t + 2) * kstep;
;             const char* a3 = a2 + kstep; const char* b3 = b2 + kstep;
;             if (last && has_next) S.a_ready(nxt);
;             if constexpr (SP2) {
;             PG8_LDB(B0, 0, 0); PG8_LDB(B1, 0, 1); PG8_SCHED; PG8_LDA(At, 0, 0); PG8_STAGE(PG8_SA(1, 1), a1 + hstep, voffA);
;             PG8_WAIT_V(8); PG8_WAIT_L(0); PG8_BAR; PG8_MMA(0, 0, At, B0); PG8_MMA(0, 1, At, B1); PG8_BAR; PG8_SCHED;
;             PG8_LDA(At, 0, 1); PG8_STAGE(PG8_SB(0, 0), b2, voffB); PG8_STAGE(PG8_SB(0, 1), b2 + hstep, voffB); PG8_STAGE(PG8_SA(0, 0), a2, voffA);
;             PG8_WAIT_V(8); PG8_WAIT_L(0); PG8_BAR; PG8_MMA(1, 0, At, B0); PG8_MMA(1, 1, At, B1); PG8_BAR; PG8_SCHED;
;             PG8_LDB(B0, 1, 0); PG8_LDB(B1, 1, 1); PG8_SCHED; PG8_LDA(At, 1, 0); PG8_STAGE(PG8_SA(0, 1), a2 + hstep, voffA);
;             PG8_WAIT_V(8); PG8_WAIT_L(0); PG8_BAR; PG8_MMA(0, 0, At, B0); PG8_MMA(0, 1, At, B1); PG8_BAR; PG8_SCHED;
;             PG8_LDA(At, 1, 1); PG8_STAGE(PG8_SB(1, 0), b3, voffB); PG8_STAGE(PG8_SB(1, 1), b3 + hstep, voffB); PG8_STAGE(PG8_SA(1, 0), a3, voffA);
;             PG8_WAIT_V(8); PG8_WAIT_L(0); PG8_BAR; PG8_MMA(1, 0, At, B0); PG8_MMA(1, 1, At, B1); PG8_BAR; PG8_SCHED;
.Lkq_2_loop:
	v_add_u32_e32 v136, 0x10000, v147
	ds_read_b128 v[148:151], v136
	ds_read_b128 v[152:155], v136 offset:1024
	ds_read_b128 v[156:159], v136 offset:2048
	ds_read_b128 v[160:163], v136 offset:3072
	ds_read_b128 v[202:205], v165 offset:16384
	ds_read_b128 v[208:211], v165 offset:17408
	ds_read_b128 v[212:215], v165 offset:18432
	ds_read_b128 v[216:219], v165 offset:19456
	ds_read_b128 v[220:223], v165 offset:20480
	ds_read_b128 v[224:227], v165 offset:21504
	ds_read_b128 v[228:231], v165 offset:22528
	ds_read_b128 v[232:235], v165 offset:23552
	v_lshl_add_u64 v[136:137], s[76:77], 0, v[0:1]
	s_add_i32 m0, s94, 0x8000
	v_lshl_add_u64 v[144:145], s[76:77], 0, v[130:131]
	global_load_lds_dwordx4 v[136:137], off
	s_add_i32 m0, s94, 0xa000
	s_nop 0
	global_load_lds_dwordx4 v[144:145], off
	v_lshl_add_u64 v[182:183], vcc, 0, v[0:1]
	s_add_i32 m0, s93, 0x1c000
	v_lshl_add_u64 v[236:237], vcc, 0, v[130:131]
	global_load_lds_dwordx4 v[182:183], off
	s_add_i32 m0, s93, 0x1e000
	s_nop 0
	global_load_lds_dwordx4 v[236:237], off
	s_cmp_lt_u32 s82, s59
	s_cselect_b32 s83, 0x80, 0
	s_add_u32 s76, s76, s83
	s_addc_u32 s77, s77, 0
	s_add_u32 vcc_lo, vcc_lo, s83
	s_addc_u32 vcc_hi, vcc_hi, 0
	s_add_i32 s82, s82, 1
	s_waitcnt vmcnt(8)
	s_waitcnt lgkmcnt(0)
	s_barrier
	s_setprio 1
	v_mfma_f32_16x16x32_bf16 v[62:65], v[148:151], v[202:205], v[62:65]
	v_mfma_f32_16x16x32_bf16 v[58:61], v[156:159], v[202:205], v[58:61]
	v_mfma_f32_16x16x32_bf16 v[46:49], v[148:151], v[212:215], v[46:49]
	v_mfma_f32_16x16x32_bf16 v[42:45], v[156:159], v[212:215], v[42:45]
	v_mfma_f32_16x16x32_bf16 v[30:33], v[148:151], v[220:223], v[30:33]
	v_mfma_f32_16x16x32_bf16 v[26:29], v[156:159], v[220:223], v[26:29]
	v_mfma_f32_16x16x32_bf16 v[14:17], v[148:151], v[228:231], v[14:17]
	v_mfma_f32_16x16x32_bf16 v[10:13], v[156:159], v[228:231], v[10:13]
	v_mfma_f32_16x16x32_bf16 v[62:65], v[152:155], v[208:211], v[62:65]
	v_mfma_f32_16x16x32_bf16 v[58:61], v[160:163], v[208:211], v[58:61]
	v_mfma_f32_16x16x32_bf16 v[46:49], v[152:155], v[216:219], v[46:49]
	v_mfma_f32_16x16x32_bf16 v[42:45], v[160:163], v[216:219], v[42:45]
	v_mfma_f32_16x16x32_bf16 v[30:33], v[152:155], v[224:227], v[30:33]
	v_mfma_f32_16x16x32_bf16 v[26:29], v[160:163], v[224:227], v[26:29]
	v_mfma_f32_16x16x32_bf16 v[14:17], v[152:155], v[232:235], v[14:17]
	v_mfma_f32_16x16x32_bf16 v[10:13], v[160:163], v[232:235], v[10:13]
	s_setprio 0
	s_barrier
	v_add_u32_e32 v136, 0x18000, v147
	ds_read_b128 v[148:151], v136
	ds_read_b128 v[152:155], v136 offset:1024
	ds_read_b128 v[156:159], v136 offset:2048
	ds_read_b128 v[160:163], v136 offset:3072
	ds_read_b128 v[202:205], v165 offset:49152
	ds_read_b128 v[208:211], v165 offset:50176
	ds_read_b128 v[212:215], v165 offset:51200
	ds_read_b128 v[216:219], v165 offset:52224
	ds_read_b128 v[220:223], v165 offset:53248
	ds_read_b128 v[224:227], v165 offset:54272
	ds_read_b128 v[228:231], v165 offset:55296
	ds_read_b128 v[232:235], v165 offset:56320
	v_lshl_add_u64 v[136:137], s[76:77], 0, v[0:1]
	s_add_i32 m0, s94, 0x4000
	v_lshl_add_u64 v[144:145], s[76:77], 0, v[130:131]
	global_load_lds_dwordx4 v[136:137], off
	s_add_i32 m0, s94, 0x6000
	s_nop 0
	global_load_lds_dwordx4 v[144:145], off
	v_lshl_add_u64 v[182:183], vcc, 0, v[0:1]
	s_add_i32 m0, s93, 0x10000
	v_lshl_add_u64 v[236:237], vcc, 0, v[130:131]
	global_load_lds_dwordx4 v[182:183], off
	s_add_i32 m0, s93, 0x12000
	s_nop 0
	global_load_lds_dwordx4 v[236:237], off
	s_cmp_lt_u32 s82, s59
	s_cselect_b32 s83, 0x80, 0
	s_add_u32 s76, s76, s83
	s_addc_u32 s77, s77, 0
	s_add_u32 vcc_lo, vcc_lo, s83
	s_addc_u32 vcc_hi, vcc_hi, 0
	s_add_i32 s82, s82, 1
	s_waitcnt vmcnt(8)
	s_waitcnt lgkmcnt(0)
	s_barrier
	s_setprio 1
	v_mfma_f32_16x16x32_bf16 v[62:65], v[148:151], v[202:205], v[62:65]
	v_mfma_f32_16x16x32_bf16 v[58:61], v[156:159], v[202:205], v[58:61]
	v_mfma_f32_16x16x32_bf16 v[46:49], v[148:151], v[212:215], v[46:49]
	v_mfma_f32_16x16x32_bf16 v[42:45], v[156:159], v[212:215], v[42:45]
	v_mfma_f32_16x16x32_bf16 v[30:33], v[148:151], v[220:223], v[30:33]
	v_mfma_f32_16x16x32_bf16 v[26:29], v[156:159], v[220:223], v[26:29]
	v_mfma_f32_16x16x32_bf16 v[14:17], v[148:151], v[228:231], v[14:17]
	v_mfma_f32_16x16x32_bf16 v[10:13], v[156:159], v[228:231], v[10:13]
	v_mfma_f32_16x16x32_bf16 v[62:65], v[152:155], v[208:211], v[62:65]
	v_mfma_f32_16x16x32_bf16 v[58:61], v[160:163], v[208:211], v[58:61]
	v_mfma_f32_16x16x32_bf16 v[46:49], v[152:155], v[216:219], v[46:49]
	v_mfma_f32_16x16x32_bf16 v[42:45], v[160:163], v[216:219], v[42:45]
	v_mfma_f32_16x16x32_bf16 v[30:33], v[152:155], v[224:227], v[30:33]
	v_mfma_f32_16x16x32_bf16 v[26:29], v[160:163], v[224:227], v[26:29]
	v_mfma_f32_16x16x32_bf16 v[14:17], v[152:155], v[232:235], v[14:17]
	v_mfma_f32_16x16x32_bf16 v[10:13], v[160:163], v[232:235], v[10:13]
	s_setprio 0
	s_barrier
	v_add_u32_e32 v136, 0x14000, v147
	ds_read_b128 v[148:151], v136
	ds_read_b128 v[152:155], v136 offset:1024
	ds_read_b128 v[156:159], v136 offset:2048
	ds_read_b128 v[160:163], v136 offset:3072
	ds_read_b128 v[202:205], v165
	ds_read_b128 v[208:211], v165 offset:1024
	ds_read_b128 v[212:215], v165 offset:2048
	ds_read_b128 v[216:219], v165 offset:3072
	ds_read_b128 v[220:223], v165 offset:4096
	ds_read_b128 v[224:227], v165 offset:5120
	ds_read_b128 v[228:231], v165 offset:6144
	ds_read_b128 v[232:235], v165 offset:7168
	v_lshl_add_u64 v[136:137], s[76:77], 0, v[0:1]
	s_add_i32 m0, s94, 0xc000
	v_lshl_add_u64 v[144:145], s[76:77], 0, v[130:131]
	global_load_lds_dwordx4 v[136:137], off
	s_add_i32 m0, s94, 0xe000
	s_nop 0
	global_load_lds_dwordx4 v[144:145], off
	v_lshl_add_u64 v[182:183], vcc, 0, v[0:1]
	s_add_i32 m0, s93, 0x18000
	v_lshl_add_u64 v[236:237], vcc, 0, v[130:131]
	global_load_lds_dwordx4 v[182:183], off
	s_add_i32 m0, s93, 0x1a000
	s_nop 0
	global_load_lds_dwordx4 v[236:237], off
	s_cmp_lt_u32 s82, s59
	s_cselect_b32 s83, 0x80, 0
	s_add_u32 s76, s76, s83
	s_addc_u32 s77, s77, 0
	s_add_u32 vcc_lo, vcc_lo, s83
	s_addc_u32 vcc_hi, vcc_hi, 0
	s_add_i32 s82, s82, 1
	s_waitcnt vmcnt(8)
	s_waitcnt lgkmcnt(0)
	s_barrier
; #define PG8_STAGE(bufoff, gbase, voff) do { _Pragma("unroll") for (int _i = 0; _i < 2; ++_i) \
;         __builtin_amdgcn_global_load_lds((const unsigned*)((const char*)(gbase) + (voff)[_i]), (PG8_LAS unsigned*)(lds + (bufoff) + ldsw + _i * 8192), 16, 0, 0); } while (0)
; #define PG8_BAR __builtin_amdgcn_s_barrier()
; template <class Epi, class Sched, bool ALIGN_EPI = false, bool SP2 = false>
; __device__ __forceinline__ void gemm_phase(PG8_LAS unsigned char* lds, const Gemm g, const Sched& S, const Epi& E) {
;     ...
;         PG8_STAGE(PG8_SB(0, 0), cB, voffB); PG8_STAGE(PG8_SB(0, 1), cB + hstep, voffB); PG8_STAGE(PG8_SA(0, 0), cA, voffA); PG8_STAGE(PG8_SA(0, 1), cA + hstep, voffA);
;         if (wr == 1) PG8_BAR;
;         PG8_WAIT_V(2); PG8_BAR;
;         PG8_STAGE(PG8_SB(1, 0), cB + kstep, voffB); PG8_STAGE(PG8_SA(1, 0), cA + kstep, voffA); PG8_STAGE(PG8_SB(1, 1), cB + hstep + kstep, voffB);
;     ...
;         for (int t = 0; t < nt; t += 2) {
;             const bool last = (t == nt - 2);
;             const char* a1 = cA + (size_t)(t + 1) * kstep;
;             const char* a2 = last ? nA : cA + (size_t)(t + 2) * kstep; const char* b2 = last ? nB : cB + (size_t)(t + 2) * kstep;
;             const char* a3 = a2 + kstep; const char* b3 = b2 + kstep;
;             if (last && has_next) S.a_ready(nxt);
;             if constexpr (SP2) {
;             PG8_LDB(B0, 0, 0); PG8_LDB(B1, 0, 1); PG8_SCHED; PG8_LDA(At, 0, 0); PG8_STAGE(PG8_SA(1, 1), a1 + hstep, voffA);
;             PG8_WAIT_V(8); PG8_WAIT_L(0); PG8_BAR; PG8_MMA(0, 0, At, B0); PG8_MMA(0, 1, At, B1); PG8_BAR; PG8_SCHED;
;             PG8_LDA(At, 0, 1); PG8_STAGE(PG8_SB(0, 0), b2, voffB); PG8_STAGE(PG8_SB(0, 1), b2 + hstep, voffB); PG8_STAGE(PG8_SA(0, 0), a2, voffA);
;             PG8_WAIT_V(8); PG8_WAIT_L(0); PG8_BAR; PG8_MMA(1, 0, At, B0); PG8_MMA(1, 1, At, B1); PG8_BAR; PG8_SCHED;
;             PG8_LDB(B0, 1, 0); PG8_LDB(B1, 1, 1); PG8_SCHED; PG8_LDA(At, 1, 0); PG8_STAGE(PG8_SA(0, 1), a2 + hstep, voffA);
;             PG8_WAIT_V(8); PG8_WAIT_L(0); PG8_BAR; PG8_MMA(0, 0, At, B0); PG8_MMA(0, 1, At, B1); PG8_BAR; PG8_SCHED;
;             PG8_LDA(At, 1, 1); PG8_STAGE(PG8_SB(1, 0), b3, voffB); PG8_STAGE(PG8_SB(1, 1), b3 + hstep, voffB); PG8_STAGE(PG8_SA(1, 0), a3, voffA);
;             PG8_WAIT_V(8); PG8_WAIT_L(0); PG8_BAR; PG8_MMA(1, 0, At, B0); PG8_MMA(1, 1, At, B1); PG8_BAR; PG8_SCHED;
	s_setprio 1
	v_mfma_f32_16x16x32_bf16 v[62:65], v[148:151], v[202:205], v[62:65]
	v_mfma_f32_16x16x32_bf16 v[58:61], v[156:159], v[202:205], v[58:61]
	v_mfma_f32_16x16x32_bf16 v[46:49], v[148:151], v[212:215], v[46:49]
	v_mfma_f32_16x16x32_bf16 v[42:45], v[156:159], v[212:215], v[42:45]
	v_mfma_f32_16x16x32_bf16 v[30:33], v[148:151], v[220:223], v[30:33]
	v_mfma_f32_16x16x32_bf16 v[26:29], v[156:159], v[220:223], v[26:29]
	v_mfma_f32_16x16x32_bf16 v[14:17], v[148:151], v[228:231], v[14:17]
	v_mfma_f32_16x16x32_bf16 v[10:13], v[156:159], v[228:231], v[10:13]
	v_mfma_f32_16x16x32_bf16 v[62:65], v[152:155], v[208:211], v[62:65]
	v_mfma_f32_16x16x32_bf16 v[58:61], v[160:163], v[208:211], v[58:61]
	v_mfma_f32_16x16x32_bf16 v[46:49], v[152:155], v[216:219], v[46:49]
	v_mfma_f32_16x16x32_bf16 v[42:45], v[160:163], v[216:219], v[42:45]
	v_mfma_f32_16x16x32_bf16 v[30:33], v[152:155], v[224:227], v[30:33]
	v_mfma_f32_16x16x32_bf16 v[26:29], v[160:163], v[224:227], v[26:29]
	v_mfma_f32_16x16x32_bf16 v[14:17], v[152:155], v[232:235], v[14:17]
	v_mfma_f32_16x16x32_bf16 v[10:13], v[160:163], v[232:235], v[10:13]
	s_setprio 0
	s_barrier
	v_add_u32_e32 v136, 0x1c000, v147
	ds_read_b128 v[148:151], v136
	ds_read_b128 v[152:155], v136 offset:1024
	ds_read_b128 v[156:159], v136 offset:2048
	ds_read_b128 v[160:163], v136 offset:3072
	ds_read_b128 v[202:205], v165 offset:32768
	ds_read_b128 v[208:211], v165 offset:33792
	ds_read_b128 v[212:215], v165 offset:34816
	ds_read_b128 v[216:219], v165 offset:35840
	ds_read_b128 v[220:223], v165 offset:36864
	ds_read_b128 v[224:227], v165 offset:37888
	ds_read_b128 v[228:231], v165 offset:38912
	ds_read_b128 v[232:235], v165 offset:39936
	v_lshl_add_u64 v[136:137], s[76:77], 0, v[0:1]
	s_add_i32 m0, s94, 0x0
	v_lshl_add_u64 v[144:145], s[76:77], 0, v[130:131]
	global_load_lds_dwordx4 v[136:137], off
	s_add_i32 m0, s94, 0x2000
	s_nop 0
	global_load_lds_dwordx4 v[144:145], off
	v_lshl_add_u64 v[182:183], vcc, 0, v[0:1]
	s_add_i32 m0, s93, 0x14000
	v_lshl_add_u64 v[236:237], vcc, 0, v[130:131]
	global_load_lds_dwordx4 v[182:183], off
	s_add_i32 m0, s93, 0x16000
	s_nop 0
	global_load_lds_dwordx4 v[236:237], off
	s_cmp_lt_u32 s82, s59
	s_cselect_b32 s83, 0x80, 0
	s_add_u32 s76, s76, s83
	s_addc_u32 s77, s77, 0
	s_add_u32 vcc_lo, vcc_lo, s83
	s_addc_u32 vcc_hi, vcc_hi, 0
	s_add_i32 s82, s82, 1
	s_waitcnt vmcnt(8)
	s_waitcnt lgkmcnt(0)
	s_barrier
	s_setprio 1
	v_mfma_f32_16x16x32_bf16 v[62:65], v[148:151], v[202:205], v[62:65]
	v_mfma_f32_16x16x32_bf16 v[58:61], v[156:159], v[202:205], v[58:61]
	v_mfma_f32_16x16x32_bf16 v[46:49], v[148:151], v[212:215], v[46:49]
	v_mfma_f32_16x16x32_bf16 v[42:45], v[156:159], v[212:215], v[42:45]
	v_mfma_f32_16x16x32_bf16 v[30:33], v[148:151], v[220:223], v[30:33]
	v_mfma_f32_16x16x32_bf16 v[26:29], v[156:159], v[220:223], v[26:29]
	v_mfma_f32_16x16x32_bf16 v[14:17], v[148:151], v[228:231], v[14:17]
	v_mfma_f32_16x16x32_bf16 v[10:13], v[156:159], v[228:231], v[10:13]
	v_mfma_f32_16x16x32_bf16 v[62:65], v[152:155], v[208:211], v[62:65]
	v_mfma_f32_16x16x32_bf16 v[58:61], v[160:163], v[208:211], v[58:61]
	v_mfma_f32_16x16x32_bf16 v[46:49], v[152:155], v[216:219], v[46:49]
	v_mfma_f32_16x16x32_bf16 v[42:45], v[160:163], v[216:219], v[42:45]
	v_mfma_f32_16x16x32_bf16 v[30:33], v[152:155], v[224:227], v[30:33]
	v_mfma_f32_16x16x32_bf16 v[26:29], v[160:163], v[224:227], v[26:29]
	v_mfma_f32_16x16x32_bf16 v[14:17], v[152:155], v[232:235], v[14:17]
	v_mfma_f32_16x16x32_bf16 v[10:13], v[160:163], v[232:235], v[10:13]
	s_setprio 0
	s_barrier
	s_add_i32 s83, s82, -3
	s_cmp_lt_u32 s83, s79
	s_cbranch_scc1 .Lkq_2_loop
	s_mov_b64 s[76:77], s[8:9]
	s_mov_b64 vcc, s[46:47]
	v_lshl_add_u64 v[136:137], vcc, 0, v[0:1]
	s_add_i32 m0, s93, 0x10000
	v_lshl_add_u64 v[144:145], vcc, 0, v[130:131]
	global_load_lds_dwordx4 v[136:137], off
	s_add_i32 m0, s93, 0x12000
	s_nop 0
	global_load_lds_dwordx4 v[144:145], off
	s_add_u32 vcc_lo, vcc_lo, s10
	s_addc_u32 vcc_hi, vcc_hi, 0
	v_lshl_add_u64 v[136:137], vcc, 0, v[0:1]
	s_add_i32 m0, s93, 0x14000
	v_lshl_add_u64 v[144:145], vcc, 0, v[130:131]
	global_load_lds_dwordx4 v[136:137], off
	s_add_i32 m0, s93, 0x16000
	s_nop 0
	global_load_lds_dwordx4 v[144:145], off
	v_lshl_add_u64 v[136:137], s[76:77], 0, v[0:1]
	s_add_i32 m0, s94, 0x0
	v_lshl_add_u64 v[144:145], s[76:77], 0, v[130:131]
	global_load_lds_dwordx4 v[136:137], off
	s_add_i32 m0, s94, 0x2000
	s_nop 0
	global_load_lds_dwordx4 v[144:145], off
	s_add_u32 s76, s76, s10
	s_addc_u32 s77, s77, 0
	v_lshl_add_u64 v[136:137], s[76:77], 0, v[0:1]
	s_add_i32 m0, s94, 0x4000
	v_lshl_add_u64 v[144:145], s[76:77], 0, v[130:131]
	global_load_lds_dwordx4 v[136:137], off
	s_add_i32 m0, s94, 0x6000
	s_nop 0
	global_load_lds_dwordx4 v[144:145], off
	s_add_u32 s76, s8, 0x80
	s_addc_u32 s77, s9, 0
	s_add_u32 vcc_lo, s46, 0x80
	s_addc_u32 vcc_hi, s47, 0
	v_lshl_add_u64 v[136:137], vcc, 0, v[0:1]
	s_add_i32 m0, s93, 0x18000
	v_lshl_add_u64 v[144:145], vcc, 0, v[130:131]
	global_load_lds_dwordx4 v[136:137], off
	s_add_i32 m0, s93, 0x1a000
	s_nop 0
	global_load_lds_dwordx4 v[144:145], off
	s_add_u32 vcc_lo, vcc_lo, s10
	s_addc_u32 vcc_hi, vcc_hi, 0
	v_lshl_add_u64 v[136:137], vcc, 0, v[0:1]
	s_add_i32 m0, s93, 0x1c000
	v_lshl_add_u64 v[144:145], vcc, 0, v[130:131]
	global_load_lds_dwordx4 v[136:137], off
	s_add_i32 m0, s93, 0x1e000
	s_nop 0
	global_load_lds_dwordx4 v[144:145], off
	v_lshl_add_u64 v[136:137], s[76:77], 0, v[0:1]
	s_add_i32 m0, s94, 0x8000
	v_lshl_add_u64 v[144:145], s[76:77], 0, v[130:131]
	global_load_lds_dwordx4 v[136:137], off
	s_add_i32 m0, s94, 0xa000
	s_nop 0
	global_load_lds_dwordx4 v[144:145], off
	s_branch .Lkq_exit

; #define PG8_STAGE(bufoff, gbase, voff) do { _Pragma("unroll") for (int _i = 0; _i < 2; ++_i) \
;         __builtin_amdgcn_global_load_lds((const unsigned*)((const char*)(gbase) + (voff)[_i]), (PG8_LAS unsigned*)(lds + (bufoff) + ldsw + _i * 8192), 16, 0, 0); } while (0)
; #define PG8_LDA(dst, b, h) do { _Pragma("unroll") for (int m = 0; m < 4; ++m) _Pragma("unroll") for (int k = 0; k < 2; ++k) dst[m][k] = *(const PG8_LAS bf16x8*)(lds + PG8_SA(b, h) + aoff + m * 2048 + k * 1024); } while (0)
; #define PG8_LDB(dst, b, h) do { _Pragma("unroll") for (int n = 0; n < 2; ++n) _Pragma("unroll") for (int k = 0; k < 2; ++k) dst[n][k] = *(const PG8_LAS bf16x8*)(lds + PG8_SB(b, h) + boff + n * 2048 + k * 1024); } while (0)
; template <class Epi, class Sched, bool ALIGN_EPI = false, bool SP2 = false>
; __device__ __forceinline__ void gemm_phase(PG8_LAS unsigned char* lds, const Gemm g, const Sched& S, const Epi& E) {
;     ...
;         for (int t = 0; t < nt; t += 2) {
;             const bool last = (t == nt - 2);
;             const char* a1 = cA + (size_t)(t + 1) * kstep;
;             const char* a2 = last ? nA : cA + (size_t)(t + 2) * kstep; const char* b2 = last ? nB : cB + (size_t)(t + 2) * kstep;
;             const char* a3 = a2 + kstep; const char* b3 = b2 + kstep;
;             if (last && has_next) S.a_ready(nxt);
;             if constexpr (SP2) {
;             PG8_LDB(B0, 0, 0); PG8_LDB(B1, 0, 1); PG8_SCHED; PG8_LDA(At, 0, 0); PG8_STAGE(PG8_SA(1, 1), a1 + hstep, voffA);
;             PG8_WAIT_V(8); PG8_WAIT_L(0); PG8_BAR; PG8_MMA(0, 0, At, B0); PG8_MMA(0, 1, At, B1); PG8_BAR; PG8_SCHED;
;             PG8_LDA(At, 0, 1); PG8_STAGE(PG8_SB(0, 0), b2, voffB); PG8_STAGE(PG8_SB(0, 1), b2 + hstep, voffB); PG8_STAGE(PG8_SA(0, 0), a2, voffA);
;             PG8_WAIT_V(8); PG8_WAIT_L(0); PG8_BAR; PG8_MMA(1, 0, At, B0); PG8_MMA(1, 1, At, B1); PG8_BAR; PG8_SCHED;
;             PG8_LDB(B0, 1, 0); PG8_LDB(B1, 1, 1); PG8_SCHED; PG8_LDA(At, 1, 0); PG8_STAGE(PG8_SA(0, 1), a2 + hstep, voffA);
;             PG8_WAIT_V(8); PG8_WAIT_L(0); PG8_BAR; PG8_MMA(0, 0, At, B0); PG8_MMA(0, 1, At, B1); PG8_BAR; PG8_SCHED;
;             PG8_LDA(At, 1, 1); PG8_STAGE(PG8_SB(1, 0), b3, voffB); PG8_STAGE(PG8_SB(1, 1), b3 + hstep, voffB); PG8_STAGE(PG8_SA(1, 0), a3, voffA);
;             PG8_WAIT_V(8); PG8_WAIT_L(0); PG8_BAR; PG8_MMA(1, 0, At, B0); PG8_MMA(1, 1, At, B1); PG8_BAR; PG8_SCHED;
.Lkq_3_loop:
	v_add_u32_e32 v136, 0x14000, v147
	ds_read_b128 v[166:169], v136
	ds_read_b128 v[170:173], v136 offset:1024
	ds_read_b128 v[174:177], v136 offset:2048
	ds_read_b128 v[178:181], v136 offset:3072
	ds_read_b128 v[202:205], v165
	ds_read_b128 v[208:211], v165 offset:1024
	ds_read_b128 v[212:215], v165 offset:2048
	ds_read_b128 v[216:219], v165 offset:3072
	ds_read_b128 v[220:223], v165 offset:4096
	ds_read_b128 v[224:227], v165 offset:5120
	ds_read_b128 v[228:231], v165 offset:6144
	ds_read_b128 v[232:235], v165 offset:7168
	v_lshl_add_u64 v[136:137], s[76:77], 0, v[0:1]
	s_add_i32 m0, s94, 0xc000
	v_lshl_add_u64 v[144:145], s[76:77], 0, v[130:131]
	global_load_lds_dwordx4 v[136:137], off
	s_add_i32 m0, s94, 0xe000
	s_nop 0
	global_load_lds_dwordx4 v[144:145], off
	v_lshl_add_u64 v[182:183], vcc, 0, v[0:1]
	s_add_i32 m0, s93, 0x18000
	v_lshl_add_u64 v[236:237], vcc, 0, v[130:131]
	global_load_lds_dwordx4 v[182:183], off
	s_add_i32 m0, s93, 0x1a000
	s_nop 0
	global_load_lds_dwordx4 v[236:237], off
	s_cmp_lt_u32 s82, s59
	s_cselect_b32 s83, 0x80, 0
	s_add_u32 s76, s76, s83
	s_addc_u32 s77, s77, 0
	s_add_u32 vcc_lo, vcc_lo, s83
	s_addc_u32 vcc_hi, vcc_hi, 0
	s_add_i32 s82, s82, 1
	s_waitcnt vmcnt(8)
	s_waitcnt lgkmcnt(0)
	s_barrier
	s_setprio 1
	v_mfma_f32_16x16x32_bf16 v[118:121], v[166:169], v[202:205], v[118:121]
	v_mfma_f32_16x16x32_bf16 v[114:117], v[174:177], v[202:205], v[114:117]
	v_mfma_f32_16x16x32_bf16 v[102:105], v[166:169], v[212:215], v[102:105]
	v_mfma_f32_16x16x32_bf16 v[98:101], v[174:177], v[212:215], v[98:101]
	v_mfma_f32_16x16x32_bf16 v[86:89], v[166:169], v[220:223], v[86:89]
	v_mfma_f32_16x16x32_bf16 v[82:85], v[174:177], v[220:223], v[82:85]
	v_mfma_f32_16x16x32_bf16 v[70:73], v[166:169], v[228:231], v[70:73]
	v_mfma_f32_16x16x32_bf16 v[66:69], v[174:177], v[228:231], v[66:69]
	v_mfma_f32_16x16x32_bf16 v[118:121], v[170:173], v[208:211], v[118:121]
	v_mfma_f32_16x16x32_bf16 v[114:117], v[178:181], v[208:211], v[114:117]
	v_mfma_f32_16x16x32_bf16 v[102:105], v[170:173], v[216:219], v[102:105]
	v_mfma_f32_16x16x32_bf16 v[98:101], v[178:181], v[216:219], v[98:101]
	v_mfma_f32_16x16x32_bf16 v[86:89], v[170:173], v[224:227], v[86:89]
	v_mfma_f32_16x16x32_bf16 v[82:85], v[178:181], v[224:227], v[82:85]
	v_mfma_f32_16x16x32_bf16 v[70:73], v[170:173], v[232:235], v[70:73]
	v_mfma_f32_16x16x32_bf16 v[66:69], v[178:181], v[232:235], v[66:69]
	s_setprio 0
	s_barrier
	v_add_u32_e32 v136, 0x1c000, v147
	ds_read_b128 v[166:169], v136
	ds_read_b128 v[170:173], v136 offset:1024
	ds_read_b128 v[174:177], v136 offset:2048
	ds_read_b128 v[178:181], v136 offset:3072
	ds_read_b128 v[202:205], v165 offset:32768
	ds_read_b128 v[208:211], v165 offset:33792
	ds_read_b128 v[212:215], v165 offset:34816
	ds_read_b128 v[216:219], v165 offset:35840
	ds_read_b128 v[220:223], v165 offset:36864
	ds_read_b128 v[224:227], v165 offset:37888
	ds_read_b128 v[228:231], v165 offset:38912
	ds_read_b128 v[232:235], v165 offset:39936
	v_lshl_add_u64 v[136:137], s[76:77], 0, v[0:1]
	s_add_i32 m0, s94, 0x0
	v_lshl_add_u64 v[144:145], s[76:77], 0, v[130:131]
	global_load_lds_dwordx4 v[136:137], off
	s_add_i32 m0, s94, 0x2000
	s_nop 0
	global_load_lds_dwordx4 v[144:145], off
	v_lshl_add_u64 v[182:183], vcc, 0, v[0:1]
	s_add_i32 m0, s93, 0x14000
	v_lshl_add_u64 v[236:237], vcc, 0, v[130:131]
	global_load_lds_dwordx4 v[182:183], off
	s_add_i32 m0, s93, 0x16000
	s_nop 0
	global_load_lds_dwordx4 v[236:237], off
	s_cmp_lt_u32 s82, s59
	s_cselect_b32 s83, 0x80, 0
	s_add_u32 s76, s76, s83
	s_addc_u32 s77, s77, 0
	s_add_u32 vcc_lo, vcc_lo, s83
	s_addc_u32 vcc_hi, vcc_hi, 0
	s_add_i32 s82, s82, 1
	s_waitcnt vmcnt(8)
	s_waitcnt lgkmcnt(0)
	s_barrier
	s_setprio 1
	v_mfma_f32_16x16x32_bf16 v[118:121], v[166:169], v[202:205], v[118:121]
	v_mfma_f32_16x16x32_bf16 v[114:117], v[174:177], v[202:205], v[114:117]
	v_mfma_f32_16x16x32_bf16 v[102:105], v[166:169], v[212:215], v[102:105]
	v_mfma_f32_16x16x32_bf16 v[98:101], v[174:177], v[212:215], v[98:101]
	v_mfma_f32_16x16x32_bf16 v[86:89], v[166:169], v[220:223], v[86:89]
	v_mfma_f32_16x16x32_bf16 v[82:85], v[174:177], v[220:223], v[82:85]
	v_mfma_f32_16x16x32_bf16 v[70:73], v[166:169], v[228:231], v[70:73]
	v_mfma_f32_16x16x32_bf16 v[66:69], v[174:177], v[228:231], v[66:69]
	v_mfma_f32_16x16x32_bf16 v[118:121], v[170:173], v[208:211], v[118:121]
	v_mfma_f32_16x16x32_bf16 v[114:117], v[178:181], v[208:211], v[114:117]
	v_mfma_f32_16x16x32_bf16 v[102:105], v[170:173], v[216:219], v[102:105]
	v_mfma_f32_16x16x32_bf16 v[98:101], v[178:181], v[216:219], v[98:101]
	v_mfma_f32_16x16x32_bf16 v[86:89], v[170:173], v[224:227], v[86:89]
	v_mfma_f32_16x16x32_bf16 v[82:85], v[178:181], v[224:227], v[82:85]
	v_mfma_f32_16x16x32_bf16 v[70:73], v[170:173], v[232:235], v[70:73]
	v_mfma_f32_16x16x32_bf16 v[66:69], v[178:181], v[232:235], v[66:69]
	s_setprio 0
	s_barrier
	v_add_u32_e32 v136, 0x10000, v147
	ds_read_b128 v[166:169], v136
	ds_read_b128 v[170:173], v136 offset:1024
	ds_read_b128 v[174:177], v136 offset:2048
	ds_read_b128 v[178:181], v136 offset:3072
	ds_read_b128 v[202:205], v165 offset:16384
	ds_read_b128 v[208:211], v165 offset:17408
	ds_read_b128 v[212:215], v165 offset:18432
	ds_read_b128 v[216:219], v165 offset:19456
	ds_read_b128 v[220:223], v165 offset:20480
	ds_read_b128 v[224:227], v165 offset:21504
	ds_read_b128 v[228:231], v165 offset:22528
	ds_read_b128 v[232:235], v165 offset:23552
	v_lshl_add_u64 v[136:137], s[76:77], 0, v[0:1]
	s_add_i32 m0, s94, 0x8000
	v_lshl_add_u64 v[144:145], s[76:77], 0, v[130:131]
	global_load_lds_dwordx4 v[136:137], off
	s_add_i32 m0, s94, 0xa000
	s_nop 0
	global_load_lds_dwordx4 v[144:145], off
	v_lshl_add_u64 v[182:183], vcc, 0, v[0:1]
	s_add_i32 m0, s93, 0x1c000
	v_lshl_add_u64 v[236:237], vcc, 0, v[130:131]
	global_load_lds_dwordx4 v[182:183], off
	s_add_i32 m0, s93, 0x1e000
	s_nop 0
	global_load_lds_dwordx4 v[236:237], off
	s_cmp_lt_u32 s82, s59
	s_cselect_b32 s83, 0x80, 0
	s_add_u32 s76, s76, s83
	s_addc_u32 s77, s77, 0
	s_add_u32 vcc_lo, vcc_lo, s83
	s_addc_u32 vcc_hi, vcc_hi, 0
	s_add_i32 s82, s82, 1
	s_waitcnt vmcnt(8)
	s_waitcnt lgkmcnt(0)
	s_barrier
; #define PG8_STAGE(bufoff, gbase, voff) do { _Pragma("unroll") for (int _i = 0; _i < 2; ++_i) \
;         __builtin_amdgcn_global_load_lds((const unsigned*)((const char*)(gbase) + (voff)[_i]), (PG8_LAS unsigned*)(lds + (bufoff) + ldsw + _i * 8192), 16, 0, 0); } while (0)
; #define PG8_LDA(dst, b, h) do { _Pragma("unroll") for (int m = 0; m < 4; ++m) _Pragma("unroll") for (int k = 0; k < 2; ++k) dst[m][k] = *(const PG8_LAS bf16x8*)(lds + PG8_SA(b, h) + aoff + m * 2048 + k * 1024); } while (0)
; #define PG8_LDB(dst, b, h) do { _Pragma("unroll") for (int n = 0; n < 2; ++n) _Pragma("unroll") for (int k = 0; k < 2; ++k) dst[n][k] = *(const PG8_LAS bf16x8*)(lds + PG8_SB(b, h) + boff + n * 2048 + k * 1024); } while (0)
; template <class Epi, class Sched, bool ALIGN_EPI = false, bool SP2 = false>
; __device__ __forceinline__ void gemm_phase(PG8_LAS unsigned char* lds, const Gemm g, const Sched& S, const Epi& E) {
;     ...
;         PG8_STAGE(PG8_SB(0, 0), cB, voffB); PG8_STAGE(PG8_SB(0, 1), cB + hstep, voffB); PG8_STAGE(PG8_SA(0, 0), cA, voffA); PG8_STAGE(PG8_SA(0, 1), cA + hstep, voffA);
;         if (wr == 1) PG8_BAR;
;         PG8_WAIT_V(2); PG8_BAR;
;         PG8_STAGE(PG8_SB(1, 0), cB + kstep, voffB); PG8_STAGE(PG8_SA(1, 0), cA + kstep, voffA); PG8_STAGE(PG8_SB(1, 1), cB + hstep + kstep, voffB);
;         PG8_WAIT_V(6); PG8_BAR;
;     ...
;             PG8_LDB(B0, 0, 0); PG8_LDB(B1, 0, 1); PG8_SCHED; PG8_LDA(At, 0, 0); PG8_STAGE(PG8_SA(1, 1), a1 + hstep, voffA);
;             PG8_WAIT_V(8); PG8_WAIT_L(0); PG8_BAR; PG8_MMA(0, 0, At, B0); PG8_MMA(0, 1, At, B1); PG8_BAR; PG8_SCHED;
;             PG8_LDA(At, 0, 1); PG8_STAGE(PG8_SB(0, 0), b2, voffB); PG8_STAGE(PG8_SB(0, 1), b2 + hstep, voffB); PG8_STAGE(PG8_SA(0, 0), a2, voffA);
;             PG8_WAIT_V(8); PG8_WAIT_L(0); PG8_BAR; PG8_MMA(1, 0, At, B0); PG8_MMA(1, 1, At, B1); PG8_BAR; PG8_SCHED;
;             PG8_LDB(B0, 1, 0); PG8_LDB(B1, 1, 1); PG8_SCHED; PG8_LDA(At, 1, 0); PG8_STAGE(PG8_SA(0, 1), a2 + hstep, voffA);
;             PG8_WAIT_V(8); PG8_WAIT_L(0); PG8_BAR; PG8_MMA(0, 0, At, B0); PG8_MMA(0, 1, At, B1); PG8_BAR; PG8_SCHED;
;             PG8_LDA(At, 1, 1); PG8_STAGE(PG8_SB(1, 0), b3, voffB); PG8_STAGE(PG8_SB(1, 1), b3 + hstep, voffB); PG8_STAGE(PG8_SA(1, 0), a3, voffA);
;             PG8_WAIT_V(8); PG8_WAIT_L(0); PG8_BAR; PG8_MMA(1, 0, At, B0); PG8_MMA(1, 1, At, B1); PG8_BAR; PG8_SCHED;
	s_setprio 1
	v_mfma_f32_16x16x32_bf16 v[118:121], v[166:169], v[202:205], v[118:121]
	v_mfma_f32_16x16x32_bf16 v[114:117], v[174:177], v[202:205], v[114:117]
	v_mfma_f32_16x16x32_bf16 v[102:105], v[166:169], v[212:215], v[102:105]
	v_mfma_f32_16x16x32_bf16 v[98:101], v[174:177], v[212:215], v[98:101]
	v_mfma_f32_16x16x32_bf16 v[86:89], v[166:169], v[220:223], v[86:89]
	v_mfma_f32_16x16x32_bf16 v[82:85], v[174:177], v[220:223], v[82:85]
	v_mfma_f32_16x16x32_bf16 v[70:73], v[166:169], v[228:231], v[70:73]
	v_mfma_f32_16x16x32_bf16 v[66:69], v[174:177], v[228:231], v[66:69]
	v_mfma_f32_16x16x32_bf16 v[118:121], v[170:173], v[208:211], v[118:121]
	v_mfma_f32_16x16x32_bf16 v[114:117], v[178:181], v[208:211], v[114:117]
	v_mfma_f32_16x16x32_bf16 v[102:105], v[170:173], v[216:219], v[102:105]
	v_mfma_f32_16x16x32_bf16 v[98:101], v[178:181], v[216:219], v[98:101]
	v_mfma_f32_16x16x32_bf16 v[86:89], v[170:173], v[224:227], v[86:89]
	v_mfma_f32_16x16x32_bf16 v[82:85], v[178:181], v[224:227], v[82:85]
	v_mfma_f32_16x16x32_bf16 v[70:73], v[170:173], v[232:235], v[70:73]
	v_mfma_f32_16x16x32_bf16 v[66:69], v[178:181], v[232:235], v[66:69]
	s_setprio 0
	s_barrier
	v_add_u32_e32 v136, 0x18000, v147
	ds_read_b128 v[166:169], v136
	ds_read_b128 v[170:173], v136 offset:1024
	ds_read_b128 v[174:177], v136 offset:2048
	ds_read_b128 v[178:181], v136 offset:3072
	ds_read_b128 v[202:205], v165 offset:49152
	ds_read_b128 v[208:211], v165 offset:50176
	ds_read_b128 v[212:215], v165 offset:51200
	ds_read_b128 v[216:219], v165 offset:52224
	ds_read_b128 v[220:223], v165 offset:53248
	ds_read_b128 v[224:227], v165 offset:54272
	ds_read_b128 v[228:231], v165 offset:55296
	ds_read_b128 v[232:235], v165 offset:56320
	v_lshl_add_u64 v[136:137], s[76:77], 0, v[0:1]
	s_add_i32 m0, s94, 0x4000
	v_lshl_add_u64 v[144:145], s[76:77], 0, v[130:131]
	global_load_lds_dwordx4 v[136:137], off
	s_add_i32 m0, s94, 0x6000
	s_nop 0
	global_load_lds_dwordx4 v[144:145], off
	v_lshl_add_u64 v[182:183], vcc, 0, v[0:1]
	s_add_i32 m0, s93, 0x10000
	v_lshl_add_u64 v[236:237], vcc, 0, v[130:131]
	global_load_lds_dwordx4 v[182:183], off
	s_add_i32 m0, s93, 0x12000
	s_nop 0
	global_load_lds_dwordx4 v[236:237], off
	s_cmp_lt_u32 s82, s59
	s_cselect_b32 s83, 0x80, 0
	s_add_u32 s76, s76, s83
	s_addc_u32 s77, s77, 0
	s_add_u32 vcc_lo, vcc_lo, s83
	s_addc_u32 vcc_hi, vcc_hi, 0
	s_add_i32 s82, s82, 1
	s_waitcnt vmcnt(8)
	s_waitcnt lgkmcnt(0)
	s_barrier
	s_setprio 1
	v_mfma_f32_16x16x32_bf16 v[118:121], v[166:169], v[202:205], v[118:121]
	v_mfma_f32_16x16x32_bf16 v[114:117], v[174:177], v[202:205], v[114:117]
	v_mfma_f32_16x16x32_bf16 v[102:105], v[166:169], v[212:215], v[102:105]
	v_mfma_f32_16x16x32_bf16 v[98:101], v[174:177], v[212:215], v[98:101]
	v_mfma_f32_16x16x32_bf16 v[86:89], v[166:169], v[220:223], v[86:89]
	v_mfma_f32_16x16x32_bf16 v[82:85], v[174:177], v[220:223], v[82:85]
	v_mfma_f32_16x16x32_bf16 v[70:73], v[166:169], v[228:231], v[70:73]
	v_mfma_f32_16x16x32_bf16 v[66:69], v[174:177], v[228:231], v[66:69]
	v_mfma_f32_16x16x32_bf16 v[118:121], v[170:173], v[208:211], v[118:121]
	v_mfma_f32_16x16x32_bf16 v[114:117], v[178:181], v[208:211], v[114:117]
	v_mfma_f32_16x16x32_bf16 v[102:105], v[170:173], v[216:219], v[102:105]
	v_mfma_f32_16x16x32_bf16 v[98:101], v[178:181], v[216:219], v[98:101]
	v_mfma_f32_16x16x32_bf16 v[86:89], v[170:173], v[224:227], v[86:89]
	v_mfma_f32_16x16x32_bf16 v[82:85], v[178:181], v[224:227], v[82:85]
	v_mfma_f32_16x16x32_bf16 v[70:73], v[170:173], v[232:235], v[70:73]
	v_mfma_f32_16x16x32_bf16 v[66:69], v[178:181], v[232:235], v[66:69]
	s_setprio 0
	s_barrier
	s_add_i32 s83, s82, -3
	s_cmp_lt_u32 s83, s79
	s_cbranch_scc1 .Lkq_3_loop
	s_mov_b64 s[76:77], s[8:9]
	s_mov_b64 vcc, s[46:47]
	v_lshl_add_u64 v[136:137], vcc, 0, v[0:1]
	s_add_i32 m0, s93, 0x10000
	v_lshl_add_u64 v[144:145], vcc, 0, v[130:131]
	global_load_lds_dwordx4 v[136:137], off
	s_add_i32 m0, s93, 0x12000
	s_nop 0
	global_load_lds_dwordx4 v[144:145], off
	s_add_u32 vcc_lo, vcc_lo, s10
	s_addc_u32 vcc_hi, vcc_hi, 0
	v_lshl_add_u64 v[136:137], vcc, 0, v[0:1]
	s_add_i32 m0, s93, 0x14000
	v_lshl_add_u64 v[144:145], vcc, 0, v[130:131]
	global_load_lds_dwordx4 v[136:137], off
	s_add_i32 m0, s93, 0x16000
	s_nop 0
	global_load_lds_dwordx4 v[144:145], off
	v_lshl_add_u64 v[136:137], s[76:77], 0, v[0:1]
	s_add_i32 m0, s94, 0x0
	v_lshl_add_u64 v[144:145], s[76:77], 0, v[130:131]
	global_load_lds_dwordx4 v[136:137], off
	s_add_i32 m0, s94, 0x2000
	s_nop 0
	global_load_lds_dwordx4 v[144:145], off
	s_add_u32 s76, s76, s10
	s_addc_u32 s77, s77, 0
	v_lshl_add_u64 v[136:137], s[76:77], 0, v[0:1]
	s_add_i32 m0, s94, 0x4000
	v_lshl_add_u64 v[144:145], s[76:77], 0, v[130:131]
	global_load_lds_dwordx4 v[136:137], off
	s_add_i32 m0, s94, 0x6000
	s_nop 0
	global_load_lds_dwordx4 v[144:145], off
	s_add_u32 s76, s8, 0x80
	s_addc_u32 s77, s9, 0
	s_add_u32 vcc_lo, s46, 0x80
	s_addc_u32 vcc_hi, s47, 0
	v_lshl_add_u64 v[136:137], vcc, 0, v[0:1]
	s_add_i32 m0, s93, 0x18000
	v_lshl_add_u64 v[144:145], vcc, 0, v[130:131]
	global_load_lds_dwordx4 v[136:137], off
	s_add_i32 m0, s93, 0x1a000
	s_nop 0
	global_load_lds_dwordx4 v[144:145], off
	s_add_u32 vcc_lo, vcc_lo, s10
	s_addc_u32 vcc_hi, vcc_hi, 0
	v_lshl_add_u64 v[136:137], vcc, 0, v[0:1]
	s_add_i32 m0, s93, 0x1c000
	v_lshl_add_u64 v[144:145], vcc, 0, v[130:131]
	global_load_lds_dwordx4 v[136:137], off
	s_add_i32 m0, s93, 0x1e000
	s_nop 0
	global_load_lds_dwordx4 v[144:145], off
	v_lshl_add_u64 v[136:137], s[76:77], 0, v[0:1]
	s_add_i32 m0, s94, 0x8000
	v_lshl_add_u64 v[144:145], s[76:77], 0, v[130:131]
	global_load_lds_dwordx4 v[136:137], off
	s_add_i32 m0, s94, 0xa000
	s_nop 0
	global_load_lds_dwordx4 v[144:145], off
	s_branch .Lkq_exit

; #define PG8_STAGE(bufoff, gbase, voff) do { _Pragma("unroll") for (int _i = 0; _i < 2; ++_i) \
;         __builtin_amdgcn_global_load_lds((const unsigned*)((const char*)(gbase) + (voff)[_i]), (PG8_LAS unsigned*)(lds + (bufoff) + ldsw + _i * 8192), 16, 0, 0); } while (0)
; #define PG8_LDA(dst, b, h) do { _Pragma("unroll") for (int m = 0; m < 4; ++m) _Pragma("unroll") for (int k = 0; k < 2; ++k) dst[m][k] = *(const PG8_LAS bf16x8*)(lds + PG8_SA(b, h) + aoff + m * 2048 + k * 1024); } while (0)
; #define PG8_LDB(dst, b, h) do { _Pragma("unroll") for (int n = 0; n < 2; ++n) _Pragma("unroll") for (int k = 0; k < 2; ++k) dst[n][k] = *(const PG8_LAS bf16x8*)(lds + PG8_SB(b, h) + boff + n * 2048 + k * 1024); } while (0)
; #define PG8_MMA(ai, bj, At, Bt) do { __builtin_amdgcn_s_setprio(1); _Pragma("unroll") for (int m = 0; m < 4; ++m) _Pragma("unroll") for (int n = 0; n < 2; ++n) _Pragma("unroll") for (int k = 0; k < 2; ++k) \
;         acc[ai][bj][m][n] = __builtin_amdgcn_mfma_f32_16x16x32_bf16(Bt[n][k], At[m][k], acc[ai][bj][m][n], 0, 0, 0); __builtin_amdgcn_s_setprio(0); } while (0)
; #define PG8_WAIT_V(n) asm volatile("s_waitcnt vmcnt(" #n ")" ::: "memory")
; template <class Epi, class Sched, bool ALIGN_EPI = false, bool SP2 = false>
; __device__ __forceinline__ void gemm_phase(PG8_LAS unsigned char* lds, const Gemm g, const Sched& S, const Epi& E) {
;     ...
;             PG8_LDB(B0, 0, 0); PG8_LDB(B1, 0, 1); PG8_SCHED; PG8_LDA(At, 0, 0); PG8_STAGE(PG8_SA(1, 1), a1 + hstep, voffA);
;             PG8_WAIT_V(8); PG8_WAIT_L(0); PG8_BAR; PG8_MMA(0, 0, At, B0); PG8_MMA(0, 1, At, B1); PG8_BAR; PG8_SCHED;
;             PG8_LDA(At, 0, 1); PG8_STAGE(PG8_SB(0, 0), b2, voffB); PG8_STAGE(PG8_SB(0, 1), b2 + hstep, voffB); PG8_STAGE(PG8_SA(0, 0), a2, voffA);
;             PG8_WAIT_V(8); PG8_WAIT_L(0); PG8_BAR; PG8_MMA(1, 0, At, B0); PG8_MMA(1, 1, At, B1); PG8_BAR; PG8_SCHED;
;             PG8_LDB(B0, 1, 0); PG8_LDB(B1, 1, 1); PG8_SCHED; PG8_LDA(At, 1, 0); PG8_STAGE(PG8_SA(0, 1), a2 + hstep, voffA);
;             PG8_WAIT_V(8); PG8_WAIT_L(0); PG8_BAR; PG8_MMA(0, 0, At, B0); PG8_MMA(0, 1, At, B1); PG8_BAR; PG8_SCHED;
;             PG8_LDA(At, 1, 1); PG8_STAGE(PG8_SB(1, 0), b3, voffB); PG8_STAGE(PG8_SB(1, 1), b3 + hstep, voffB); PG8_STAGE(PG8_SA(1, 0), a3, voffA);
;             PG8_WAIT_V(8); PG8_WAIT_L(0); PG8_BAR; PG8_MMA(1, 0, At, B0); PG8_MMA(1, 1, At, B1); PG8_BAR; PG8_SCHED;
.Lkq_4_loop:
	v_add_u32_e32 v136, 0x14000, v147
	ds_read_b128 v[166:169], v136
	ds_read_b128 v[170:173], v136 offset:1024
	ds_read_b128 v[174:177], v136 offset:2048
	ds_read_b128 v[178:181], v136 offset:3072
	ds_read_b128 v[202:205], v165 offset:16384
	ds_read_b128 v[208:211], v165 offset:17408
	ds_read_b128 v[212:215], v165 offset:18432
	ds_read_b128 v[216:219], v165 offset:19456
	ds_read_b128 v[220:223], v165 offset:20480
	ds_read_b128 v[224:227], v165 offset:21504
	ds_read_b128 v[228:231], v165 offset:22528
	ds_read_b128 v[232:235], v165 offset:23552
	v_lshl_add_u64 v[136:137], s[76:77], 0, v[0:1]
	s_add_i32 m0, s94, 0x8000
	v_lshl_add_u64 v[144:145], s[76:77], 0, v[130:131]
	global_load_lds_dwordx4 v[136:137], off
	s_add_i32 m0, s94, 0xa000
	s_nop 0
	global_load_lds_dwordx4 v[144:145], off
	v_lshl_add_u64 v[182:183], vcc, 0, v[0:1]
	s_add_i32 m0, s93, 0x18000
	v_lshl_add_u64 v[236:237], vcc, 0, v[130:131]
	global_load_lds_dwordx4 v[182:183], off
	s_add_i32 m0, s93, 0x1a000
	s_nop 0
	global_load_lds_dwordx4 v[236:237], off
	s_cmp_lt_u32 s82, s59
	s_cselect_b32 s83, 0x80, 0
	s_add_u32 s76, s76, s83
	s_addc_u32 s77, s77, 0
	s_add_u32 vcc_lo, vcc_lo, s83
	s_addc_u32 vcc_hi, vcc_hi, 0
	s_add_i32 s82, s82, 1
	s_waitcnt vmcnt(8)
	s_waitcnt lgkmcnt(0)
	s_barrier
	s_setprio 1
	v_mfma_f32_16x16x32_bf16 v[54:57], v[166:169], v[202:205], v[54:57]
	v_mfma_f32_16x16x32_bf16 v[50:53], v[174:177], v[202:205], v[50:53]
	v_mfma_f32_16x16x32_bf16 v[38:41], v[166:169], v[212:215], v[38:41]
	v_mfma_f32_16x16x32_bf16 v[34:37], v[174:177], v[212:215], v[34:37]
	v_mfma_f32_16x16x32_bf16 v[22:25], v[166:169], v[220:223], v[22:25]
	v_mfma_f32_16x16x32_bf16 v[18:21], v[174:177], v[220:223], v[18:21]
	v_mfma_f32_16x16x32_bf16 v[6:9], v[166:169], v[228:231], v[6:9]
	v_mfma_f32_16x16x32_bf16 v[2:5], v[174:177], v[228:231], v[2:5]
	v_mfma_f32_16x16x32_bf16 v[54:57], v[170:173], v[208:211], v[54:57]
	v_mfma_f32_16x16x32_bf16 v[50:53], v[178:181], v[208:211], v[50:53]
	v_mfma_f32_16x16x32_bf16 v[38:41], v[170:173], v[216:219], v[38:41]
	v_mfma_f32_16x16x32_bf16 v[34:37], v[178:181], v[216:219], v[34:37]
	v_mfma_f32_16x16x32_bf16 v[22:25], v[170:173], v[224:227], v[22:25]
	v_mfma_f32_16x16x32_bf16 v[18:21], v[178:181], v[224:227], v[18:21]
	v_mfma_f32_16x16x32_bf16 v[6:9], v[170:173], v[232:235], v[6:9]
	v_mfma_f32_16x16x32_bf16 v[2:5], v[178:181], v[232:235], v[2:5]
	s_setprio 0
	s_barrier
	v_add_u32_e32 v136, 0x1c000, v147
	ds_read_b128 v[166:169], v136
	ds_read_b128 v[170:173], v136 offset:1024
	ds_read_b128 v[174:177], v136 offset:2048
	ds_read_b128 v[178:181], v136 offset:3072
	ds_read_b128 v[202:205], v165 offset:49152
	ds_read_b128 v[208:211], v165 offset:50176
	ds_read_b128 v[212:215], v165 offset:51200
	ds_read_b128 v[216:219], v165 offset:52224
	ds_read_b128 v[220:223], v165 offset:53248
	ds_read_b128 v[224:227], v165 offset:54272
	ds_read_b128 v[228:231], v165 offset:55296
	ds_read_b128 v[232:235], v165 offset:56320
	v_lshl_add_u64 v[136:137], s[76:77], 0, v[0:1]
	s_add_i32 m0, s94, 0x4000
	v_lshl_add_u64 v[144:145], s[76:77], 0, v[130:131]
	global_load_lds_dwordx4 v[136:137], off
	s_add_i32 m0, s94, 0x6000
	s_nop 0
	global_load_lds_dwordx4 v[144:145], off
	v_lshl_add_u64 v[182:183], vcc, 0, v[0:1]
	s_add_i32 m0, s93, 0x14000
	v_lshl_add_u64 v[236:237], vcc, 0, v[130:131]
	global_load_lds_dwordx4 v[182:183], off
	s_add_i32 m0, s93, 0x16000
	s_nop 0
	global_load_lds_dwordx4 v[236:237], off
	s_cmp_lt_u32 s82, s59
	s_cselect_b32 s83, 0x80, 0
	s_add_u32 s76, s76, s83
	s_addc_u32 s77, s77, 0
	s_add_u32 vcc_lo, vcc_lo, s83
	s_addc_u32 vcc_hi, vcc_hi, 0
	s_add_i32 s82, s82, 1
	s_waitcnt vmcnt(8)
	s_waitcnt lgkmcnt(0)
	s_barrier
	s_setprio 1
	v_mfma_f32_16x16x32_bf16 v[54:57], v[166:169], v[202:205], v[54:57]
	v_mfma_f32_16x16x32_bf16 v[50:53], v[174:177], v[202:205], v[50:53]
	v_mfma_f32_16x16x32_bf16 v[38:41], v[166:169], v[212:215], v[38:41]
	v_mfma_f32_16x16x32_bf16 v[34:37], v[174:177], v[212:215], v[34:37]
	v_mfma_f32_16x16x32_bf16 v[22:25], v[166:169], v[220:223], v[22:25]
	v_mfma_f32_16x16x32_bf16 v[18:21], v[174:177], v[220:223], v[18:21]
	v_mfma_f32_16x16x32_bf16 v[6:9], v[166:169], v[228:231], v[6:9]
	v_mfma_f32_16x16x32_bf16 v[2:5], v[174:177], v[228:231], v[2:5]
	v_mfma_f32_16x16x32_bf16 v[54:57], v[170:173], v[208:211], v[54:57]
	v_mfma_f32_16x16x32_bf16 v[50:53], v[178:181], v[208:211], v[50:53]
	v_mfma_f32_16x16x32_bf16 v[38:41], v[170:173], v[216:219], v[38:41]
	v_mfma_f32_16x16x32_bf16 v[34:37], v[178:181], v[216:219], v[34:37]
	v_mfma_f32_16x16x32_bf16 v[22:25], v[170:173], v[224:227], v[22:25]
	v_mfma_f32_16x16x32_bf16 v[18:21], v[178:181], v[224:227], v[18:21]
	v_mfma_f32_16x16x32_bf16 v[6:9], v[170:173], v[232:235], v[6:9]
	v_mfma_f32_16x16x32_bf16 v[2:5], v[178:181], v[232:235], v[2:5]
	s_setprio 0
	s_barrier
	v_add_u32_e32 v136, 0x10000, v147
	ds_read_b128 v[166:169], v136
	ds_read_b128 v[170:173], v136 offset:1024
	ds_read_b128 v[174:177], v136 offset:2048
	ds_read_b128 v[178:181], v136 offset:3072
	ds_read_b128 v[202:205], v165
	ds_read_b128 v[208:211], v165 offset:1024
	ds_read_b128 v[212:215], v165 offset:2048
	ds_read_b128 v[216:219], v165 offset:3072
	ds_read_b128 v[220:223], v165 offset:4096
	ds_read_b128 v[224:227], v165 offset:5120
	ds_read_b128 v[228:231], v165 offset:6144
	ds_read_b128 v[232:235], v165 offset:7168
	v_lshl_add_u64 v[136:137], s[76:77], 0, v[0:1]
	s_add_i32 m0, s94, 0xc000
	v_lshl_add_u64 v[144:145], s[76:77], 0, v[130:131]
	global_load_lds_dwordx4 v[136:137], off
	s_add_i32 m0, s94, 0xe000
	s_nop 0
	global_load_lds_dwordx4 v[144:145], off
	v_lshl_add_u64 v[182:183], vcc, 0, v[0:1]
	s_add_i32 m0, s93, 0x1c000
	v_lshl_add_u64 v[236:237], vcc, 0, v[130:131]
	global_load_lds_dwordx4 v[182:183], off
	s_add_i32 m0, s93, 0x1e000
	s_nop 0
	global_load_lds_dwordx4 v[236:237], off
	s_cmp_lt_u32 s82, s59
	s_cselect_b32 s83, 0x80, 0
	s_add_u32 s76, s76, s83
	s_addc_u32 s77, s77, 0
	s_add_u32 vcc_lo, vcc_lo, s83
	s_addc_u32 vcc_hi, vcc_hi, 0
	s_add_i32 s82, s82, 1
	s_waitcnt vmcnt(8)
	s_waitcnt lgkmcnt(0)
	s_barrier
; #define PG8_STAGE(bufoff, gbase, voff) do { _Pragma("unroll") for (int _i = 0; _i < 2; ++_i) \
;         __builtin_amdgcn_global_load_lds((const unsigned*)((const char*)(gbase) + (voff)[_i]), (PG8_LAS unsigned*)(lds + (bufoff) + ldsw + _i * 8192), 16, 0, 0); } while (0)
; #define PG8_LDA(dst, b, h) do { _Pragma("unroll") for (int m = 0; m < 4; ++m) _Pragma("unroll") for (int k = 0; k < 2; ++k) dst[m][k] = *(const PG8_LAS bf16x8*)(lds + PG8_SA(b, h) + aoff + m * 2048 + k * 1024); } while (0)
; #define PG8_LDB(dst, b, h) do { _Pragma("unroll") for (int n = 0; n < 2; ++n) _Pragma("unroll") for (int k = 0; k < 2; ++k) dst[n][k] = *(const PG8_LAS bf16x8*)(lds + PG8_SB(b, h) + boff + n * 2048 + k * 1024); } while (0)
; template <class Epi, class Sched, bool ALIGN_EPI = false, bool SP2 = false>
; __device__ __forceinline__ void gemm_phase(PG8_LAS unsigned char* lds, const Gemm g, const Sched& S, const Epi& E) {
;     ...
;         PG8_STAGE(PG8_SB(0, 0), cB, voffB); PG8_STAGE(PG8_SB(0, 1), cB + hstep, voffB); PG8_STAGE(PG8_SA(0, 0), cA, voffA); PG8_STAGE(PG8_SA(0, 1), cA + hstep, voffA);
;         if (wr == 1) PG8_BAR;
;         PG8_WAIT_V(2); PG8_BAR;
;         PG8_STAGE(PG8_SB(1, 0), cB + kstep, voffB); PG8_STAGE(PG8_SA(1, 0), cA + kstep, voffA); PG8_STAGE(PG8_SB(1, 1), cB + hstep + kstep, voffB);
;         PG8_WAIT_V(6); PG8_BAR;
;     ...
;             PG8_LDB(B0, 0, 0); PG8_LDB(B1, 0, 1); PG8_SCHED; PG8_LDA(At, 0, 0); PG8_STAGE(PG8_SA(1, 1), a1 + hstep, voffA);
;             PG8_WAIT_V(8); PG8_WAIT_L(0); PG8_BAR; PG8_MMA(0, 0, At, B0); PG8_MMA(0, 1, At, B1); PG8_BAR; PG8_SCHED;
;             PG8_LDA(At, 0, 1); PG8_STAGE(PG8_SB(0, 0), b2, voffB); PG8_STAGE(PG8_SB(0, 1), b2 + hstep, voffB); PG8_STAGE(PG8_SA(0, 0), a2, voffA);
;             PG8_WAIT_V(8); PG8_WAIT_L(0); PG8_BAR; PG8_MMA(1, 0, At, B0); PG8_MMA(1, 1, At, B1); PG8_BAR; PG8_SCHED;
;             PG8_LDB(B0, 1, 0); PG8_LDB(B1, 1, 1); PG8_SCHED; PG8_LDA(At, 1, 0); PG8_STAGE(PG8_SA(0, 1), a2 + hstep, voffA);
;             PG8_WAIT_V(8); PG8_WAIT_L(0); PG8_BAR; PG8_MMA(0, 0, At, B0); PG8_MMA(0, 1, At, B1); PG8_BAR; PG8_SCHED;
;             PG8_LDA(At, 1, 1); PG8_STAGE(PG8_SB(1, 0), b3, voffB); PG8_STAGE(PG8_SB(1, 1), b3 + hstep, voffB); PG8_STAGE(PG8_SA(1, 0), a3, voffA);
;             PG8_WAIT_V(8); PG8_WAIT_L(0); PG8_BAR; PG8_MMA(1, 0, At, B0); PG8_MMA(1, 1, At, B1); PG8_BAR; PG8_SCHED;
	s_setprio 1
	v_mfma_f32_16x16x32_bf16 v[54:57], v[166:169], v[202:205], v[54:57]
	v_mfma_f32_16x16x32_bf16 v[50:53], v[174:177], v[202:205], v[50:53]
	v_mfma_f32_16x16x32_bf16 v[38:41], v[166:169], v[212:215], v[38:41]
	v_mfma_f32_16x16x32_bf16 v[34:37], v[174:177], v[212:215], v[34:37]
	v_mfma_f32_16x16x32_bf16 v[22:25], v[166:169], v[220:223], v[22:25]
	v_mfma_f32_16x16x32_bf16 v[18:21], v[174:177], v[220:223], v[18:21]
	v_mfma_f32_16x16x32_bf16 v[6:9], v[166:169], v[228:231], v[6:9]
	v_mfma_f32_16x16x32_bf16 v[2:5], v[174:177], v[228:231], v[2:5]
	v_mfma_f32_16x16x32_bf16 v[54:57], v[170:173], v[208:211], v[54:57]
	v_mfma_f32_16x16x32_bf16 v[50:53], v[178:181], v[208:211], v[50:53]
	v_mfma_f32_16x16x32_bf16 v[38:41], v[170:173], v[216:219], v[38:41]
	v_mfma_f32_16x16x32_bf16 v[34:37], v[178:181], v[216:219], v[34:37]
	v_mfma_f32_16x16x32_bf16 v[22:25], v[170:173], v[224:227], v[22:25]
	v_mfma_f32_16x16x32_bf16 v[18:21], v[178:181], v[224:227], v[18:21]
	v_mfma_f32_16x16x32_bf16 v[6:9], v[170:173], v[232:235], v[6:9]
	v_mfma_f32_16x16x32_bf16 v[2:5], v[178:181], v[232:235], v[2:5]
	s_setprio 0
	s_barrier
	v_add_u32_e32 v136, 0x18000, v147
	ds_read_b128 v[166:169], v136
	ds_read_b128 v[170:173], v136 offset:1024
	ds_read_b128 v[174:177], v136 offset:2048
	ds_read_b128 v[178:181], v136 offset:3072
	ds_read_b128 v[202:205], v165 offset:32768
	ds_read_b128 v[208:211], v165 offset:33792
	ds_read_b128 v[212:215], v165 offset:34816
	ds_read_b128 v[216:219], v165 offset:35840
	ds_read_b128 v[220:223], v165 offset:36864
	ds_read_b128 v[224:227], v165 offset:37888
	ds_read_b128 v[228:231], v165 offset:38912
	ds_read_b128 v[232:235], v165 offset:39936
	v_lshl_add_u64 v[136:137], s[76:77], 0, v[0:1]
	s_add_i32 m0, s94, 0x0
	v_lshl_add_u64 v[144:145], s[76:77], 0, v[130:131]
	global_load_lds_dwordx4 v[136:137], off
	s_add_i32 m0, s94, 0x2000
	s_nop 0
	global_load_lds_dwordx4 v[144:145], off
	v_lshl_add_u64 v[182:183], vcc, 0, v[0:1]
	s_add_i32 m0, s93, 0x10000
	v_lshl_add_u64 v[236:237], vcc, 0, v[130:131]
	global_load_lds_dwordx4 v[182:183], off
	s_add_i32 m0, s93, 0x12000
	s_nop 0
	global_load_lds_dwordx4 v[236:237], off
	s_cmp_lt_u32 s82, s59
	s_cselect_b32 s83, 0x80, 0
	s_add_u32 s76, s76, s83
	s_addc_u32 s77, s77, 0
	s_add_u32 vcc_lo, vcc_lo, s83
	s_addc_u32 vcc_hi, vcc_hi, 0
	s_add_i32 s82, s82, 1
	s_waitcnt vmcnt(8)
	s_waitcnt lgkmcnt(0)
	s_barrier
	s_setprio 1
	v_mfma_f32_16x16x32_bf16 v[54:57], v[166:169], v[202:205], v[54:57]
	v_mfma_f32_16x16x32_bf16 v[50:53], v[174:177], v[202:205], v[50:53]
	v_mfma_f32_16x16x32_bf16 v[38:41], v[166:169], v[212:215], v[38:41]
	v_mfma_f32_16x16x32_bf16 v[34:37], v[174:177], v[212:215], v[34:37]
	v_mfma_f32_16x16x32_bf16 v[22:25], v[166:169], v[220:223], v[22:25]
	v_mfma_f32_16x16x32_bf16 v[18:21], v[174:177], v[220:223], v[18:21]
	v_mfma_f32_16x16x32_bf16 v[6:9], v[166:169], v[228:231], v[6:9]
	v_mfma_f32_16x16x32_bf16 v[2:5], v[174:177], v[228:231], v[2:5]
	v_mfma_f32_16x16x32_bf16 v[54:57], v[170:173], v[208:211], v[54:57]
	v_mfma_f32_16x16x32_bf16 v[50:53], v[178:181], v[208:211], v[50:53]
	v_mfma_f32_16x16x32_bf16 v[38:41], v[170:173], v[216:219], v[38:41]
	v_mfma_f32_16x16x32_bf16 v[34:37], v[178:181], v[216:219], v[34:37]
	v_mfma_f32_16x16x32_bf16 v[22:25], v[170:173], v[224:227], v[22:25]
	v_mfma_f32_16x16x32_bf16 v[18:21], v[178:181], v[224:227], v[18:21]
	v_mfma_f32_16x16x32_bf16 v[6:9], v[170:173], v[232:235], v[6:9]
	v_mfma_f32_16x16x32_bf16 v[2:5], v[178:181], v[232:235], v[2:5]
	s_setprio 0
	s_barrier
	s_add_i32 s83, s82, -3
	s_cmp_lt_u32 s83, s79
	s_cbranch_scc1 .Lkq_4_loop
	s_mov_b64 s[76:77], s[8:9]
	s_mov_b64 vcc, s[46:47]
	v_lshl_add_u64 v[136:137], vcc, 0, v[0:1]
	s_add_i32 m0, s93, 0x10000
	v_lshl_add_u64 v[144:145], vcc, 0, v[130:131]
	global_load_lds_dwordx4 v[136:137], off
	s_add_i32 m0, s93, 0x12000
	s_nop 0
	global_load_lds_dwordx4 v[144:145], off
	s_add_u32 vcc_lo, vcc_lo, s10
	s_addc_u32 vcc_hi, vcc_hi, 0
	v_lshl_add_u64 v[136:137], vcc, 0, v[0:1]
	s_add_i32 m0, s93, 0x14000
	v_lshl_add_u64 v[144:145], vcc, 0, v[130:131]
	global_load_lds_dwordx4 v[136:137], off
	s_add_i32 m0, s93, 0x16000
	s_nop 0
	global_load_lds_dwordx4 v[144:145], off
	v_lshl_add_u64 v[136:137], s[76:77], 0, v[0:1]
	s_add_i32 m0, s94, 0x0
	v_lshl_add_u64 v[144:145], s[76:77], 0, v[130:131]
	global_load_lds_dwordx4 v[136:137], off
	s_add_i32 m0, s94, 0x2000
	s_nop 0
	global_load_lds_dwordx4 v[144:145], off
	s_add_u32 s76, s76, s10
	s_addc_u32 s77, s77, 0
	v_lshl_add_u64 v[136:137], s[76:77], 0, v[0:1]
	s_add_i32 m0, s94, 0x4000
	v_lshl_add_u64 v[144:145], s[76:77], 0, v[130:131]
	global_load_lds_dwordx4 v[136:137], off
	s_add_i32 m0, s94, 0x6000
	s_nop 0
	global_load_lds_dwordx4 v[144:145], off
	s_add_u32 s76, s8, 0x80
	s_addc_u32 s77, s9, 0
	s_add_u32 vcc_lo, s46, 0x80
	s_addc_u32 vcc_hi, s47, 0
	v_lshl_add_u64 v[136:137], vcc, 0, v[0:1]
	s_add_i32 m0, s93, 0x18000
	v_lshl_add_u64 v[144:145], vcc, 0, v[130:131]
	global_load_lds_dwordx4 v[136:137], off
	s_add_i32 m0, s93, 0x1a000
	s_nop 0
	global_load_lds_dwordx4 v[144:145], off
	s_add_u32 vcc_lo, vcc_lo, s10
	s_addc_u32 vcc_hi, vcc_hi, 0
	v_lshl_add_u64 v[136:137], vcc, 0, v[0:1]
	s_add_i32 m0, s93, 0x1c000
	v_lshl_add_u64 v[144:145], vcc, 0, v[130:131]
	global_load_lds_dwordx4 v[136:137], off
	s_add_i32 m0, s93, 0x1e000
	s_nop 0
	global_load_lds_dwordx4 v[144:145], off
	v_lshl_add_u64 v[136:137], s[76:77], 0, v[0:1]
	s_add_i32 m0, s94, 0x8000
	v_lshl_add_u64 v[144:145], s[76:77], 0, v[130:131]
	global_load_lds_dwordx4 v[136:137], off
	s_add_i32 m0, s94, 0xa000
	s_nop 0
	global_load_lds_dwordx4 v[144:145], off

;     __device__ __forceinline__ void operator()(const f32x4 (&acc)[2][2][4][2], const Unit& u, int wr, int wc, int fr, int fq) const {
;     ...
;         for (int ai = 0; ai < 2; ++ai)
; #pragma unroll
;             for (int m = 0; m < 4; ++m) {
;                 const int ro = (ai * 128 + m * 16) * DM;
;                 f32x4 s[2][2];
; #pragma unroll
;                 for (int bj = 0; bj < 2; ++bj)
; #pragma unroll
;                     for (int n = 0; n < 2; ++n) s[bj][n] = *(const f32x4*)(sp + ro + bj * 128 + n * 4);
; #pragma unroll
;                 for (int bj = 0; bj < 2; ++bj)
; #pragma unroll
;                     for (int n = 0; n < 2; ++n) *(f32x4*)(dp + ro + bj * 128 + n * 4) = s[bj][n] + gv[bj][n] * acc[ai][bj][m][n];
;                 asm volatile("" ::: "memory");
;             }
.Lkq_epiQ1:
	s_barrier
	s_mov_b64 s[48:49], 0x0
	v_lshl_add_u64 v[54:55], v[156:157], 0, s[48:49]
	v_lshl_add_u64 v[50:51], v[162:163], 0, s[48:49]
	s_mov_b64 s[48:49], 0x10000
	v_lshl_add_u64 v[38:39], v[156:157], 0, s[48:49]
	v_lshl_add_u64 v[34:35], v[162:163], 0, s[48:49]
	s_mov_b64 s[48:49], 0x20000
	v_lshl_add_u64 v[22:23], v[156:157], 0, s[48:49]
	v_lshl_add_u64 v[18:19], v[162:163], 0, s[48:49]
	s_mov_b64 s[48:49], 0x30000
	v_lshl_add_u64 v[6:7], v[156:157], 0, s[48:49]
	v_lshl_add_u64 v[2:3], v[162:163], 0, s[48:49]
	global_load_dwordx4 v[62:65], v[54:55], off
	global_load_dwordx4 v[58:61], v[54:55], off offset:16
	global_load_dwordx4 v[46:49], v[38:39], off
	global_load_dwordx4 v[42:45], v[38:39], off offset:16
	global_load_dwordx4 v[30:33], v[22:23], off
	global_load_dwordx4 v[26:29], v[22:23], off offset:16
	global_load_dwordx4 v[14:17], v[6:7], off
	global_load_dwordx4 v[10:13], v[6:7], off offset:16
	s_waitcnt vmcnt(6)
	v_pk_fma_f32 v[126:127], v[126:127], v[160:161], v[62:63]
	v_pk_fma_f32 v[128:129], v[128:129], v[158:159], v[64:65]
	v_pk_fma_f32 v[122:123], v[122:123], v[144:145], v[58:59]
	v_pk_fma_f32 v[124:125], v[124:125], v[136:137], v[60:61]
	global_store_dwordx4 v[50:51], v[126:129], off
	global_store_dwordx4 v[50:51], v[122:125], off offset:16
	s_waitcnt vmcnt(6)
	v_pk_fma_f32 v[110:111], v[110:111], v[160:161], v[46:47]
	v_pk_fma_f32 v[112:113], v[112:113], v[158:159], v[48:49]
	v_pk_fma_f32 v[106:107], v[106:107], v[144:145], v[42:43]
	v_pk_fma_f32 v[108:109], v[108:109], v[136:137], v[44:45]
	global_store_dwordx4 v[34:35], v[110:113], off
	global_store_dwordx4 v[34:35], v[106:109], off offset:16
	s_waitcnt vmcnt(6)
	v_pk_fma_f32 v[94:95], v[94:95], v[160:161], v[30:31]
	v_pk_fma_f32 v[96:97], v[96:97], v[158:159], v[32:33]
	v_pk_fma_f32 v[90:91], v[90:91], v[144:145], v[26:27]
	v_pk_fma_f32 v[92:93], v[92:93], v[136:137], v[28:29]
	global_store_dwordx4 v[18:19], v[94:97], off
	global_store_dwordx4 v[18:19], v[90:93], off offset:16
	s_waitcnt vmcnt(6)
	v_pk_fma_f32 v[78:79], v[78:79], v[160:161], v[14:15]
	v_pk_fma_f32 v[80:81], v[80:81], v[158:159], v[16:17]
	v_pk_fma_f32 v[74:75], v[74:75], v[144:145], v[10:11]
	v_pk_fma_f32 v[76:77], v[76:77], v[136:137], v[12:13]
	global_store_dwordx4 v[2:3], v[78:81], off
	global_store_dwordx4 v[2:3], v[74:77], off offset:16
	s_mov_b64 s[48:49], -1
	s_branch .Lkq_epi_end
.Lkq_epiQ2:
	s_barrier
	s_mov_b64 s[48:49], 0x80000
	v_lshl_add_u64 v[118:119], v[156:157], 0, s[48:49]
	v_lshl_add_u64 v[114:115], v[162:163], 0, s[48:49]
	s_mov_b64 s[48:49], 0x90000
	v_lshl_add_u64 v[102:103], v[156:157], 0, s[48:49]
	v_lshl_add_u64 v[98:99], v[162:163], 0, s[48:49]
	s_mov_b64 s[48:49], 0xa0000
	v_lshl_add_u64 v[86:87], v[156:157], 0, s[48:49]
	v_lshl_add_u64 v[82:83], v[162:163], 0, s[48:49]
	s_mov_b64 s[48:49], 0xb0000
	v_lshl_add_u64 v[70:71], v[156:157], 0, s[48:49]
	v_lshl_add_u64 v[66:67], v[162:163], 0, s[48:49]
	global_load_dwordx4 v[126:129], v[118:119], off
	global_load_dwordx4 v[122:125], v[118:119], off offset:16
	global_load_dwordx4 v[110:113], v[102:103], off
	global_load_dwordx4 v[106:109], v[102:103], off offset:16
	global_load_dwordx4 v[94:97], v[86:87], off
	global_load_dwordx4 v[90:93], v[86:87], off offset:16
	global_load_dwordx4 v[78:81], v[70:71], off
	global_load_dwordx4 v[74:77], v[70:71], off offset:16
	s_waitcnt vmcnt(6)
	v_pk_fma_f32 v[62:63], v[62:63], v[160:161], v[126:127]
	v_pk_fma_f32 v[64:65], v[64:65], v[158:159], v[128:129]
	v_pk_fma_f32 v[58:59], v[58:59], v[144:145], v[122:123]
	v_pk_fma_f32 v[60:61], v[60:61], v[136:137], v[124:125]
	global_store_dwordx4 v[114:115], v[62:65], off
	global_store_dwordx4 v[114:115], v[58:61], off offset:16
	s_waitcnt vmcnt(6)
	v_pk_fma_f32 v[46:47], v[46:47], v[160:161], v[110:111]
	v_pk_fma_f32 v[48:49], v[48:49], v[158:159], v[112:113]
	v_pk_fma_f32 v[42:43], v[42:43], v[144:145], v[106:107]
	v_pk_fma_f32 v[44:45], v[44:45], v[136:137], v[108:109]
	global_store_dwordx4 v[98:99], v[46:49], off
	global_store_dwordx4 v[98:99], v[42:45], off offset:16
	s_waitcnt vmcnt(6)
	v_pk_fma_f32 v[30:31], v[30:31], v[160:161], v[94:95]
	v_pk_fma_f32 v[32:33], v[32:33], v[158:159], v[96:97]
	v_pk_fma_f32 v[26:27], v[26:27], v[144:145], v[90:91]
	v_pk_fma_f32 v[28:29], v[28:29], v[136:137], v[92:93]
	global_store_dwordx4 v[82:83], v[30:33], off
	global_store_dwordx4 v[82:83], v[26:29], off offset:16
	s_waitcnt vmcnt(6)
	v_pk_fma_f32 v[14:15], v[14:15], v[160:161], v[78:79]
	v_pk_fma_f32 v[16:17], v[16:17], v[158:159], v[80:81]
	v_pk_fma_f32 v[10:11], v[10:11], v[144:145], v[74:75]
	v_pk_fma_f32 v[12:13], v[12:13], v[136:137], v[76:77]
	global_store_dwordx4 v[66:67], v[14:17], off
	global_store_dwordx4 v[66:67], v[10:13], off offset:16
	s_mov_b64 s[48:49], -1
	s_branch .Lkq_epi_end
;     __device__ __forceinline__ void operator()(const f32x4 (&acc)[2][2][4][2], const Unit& u, int wr, int wc, int fr, int fq) const {
;     ...
;         for (int ai = 0; ai < 2; ++ai)
; #pragma unroll
;             for (int m = 0; m < 4; ++m) {
;                 const int ro = (ai * 128 + m * 16) * DM;
;                 f32x4 s[2][2];
; #pragma unroll
;                 for (int bj = 0; bj < 2; ++bj)
; #pragma unroll
;                     for (int n = 0; n < 2; ++n) s[bj][n] = *(const f32x4*)(sp + ro + bj * 128 + n * 4);
; #pragma unroll
;                 for (int bj = 0; bj < 2; ++bj)
; #pragma unroll
;                     for (int n = 0; n < 2; ++n) *(f32x4*)(dp + ro + bj * 128 + n * 4) = s[bj][n] + gv[bj][n] * acc[ai][bj][m][n];
;                 asm volatile("" ::: "memory");
;             }
.Lkq_epiQ3:
	s_barrier
	s_mov_b64 s[48:49], 0x200
	v_lshl_add_u64 v[54:55], v[156:157], 0, s[48:49]
	v_lshl_add_u64 v[50:51], v[162:163], 0, s[48:49]
	s_mov_b64 s[48:49], 0x10200
	v_lshl_add_u64 v[38:39], v[156:157], 0, s[48:49]
	v_lshl_add_u64 v[34:35], v[162:163], 0, s[48:49]
	s_mov_b64 s[48:49], 0x20200
	v_lshl_add_u64 v[22:23], v[156:157], 0, s[48:49]
	v_lshl_add_u64 v[18:19], v[162:163], 0, s[48:49]
	s_mov_b64 s[48:49], 0x30200
	v_lshl_add_u64 v[6:7], v[156:157], 0, s[48:49]
	v_lshl_add_u64 v[2:3], v[162:163], 0, s[48:49]
	global_load_dwordx4 v[62:65], v[54:55], off
	global_load_dwordx4 v[58:61], v[54:55], off offset:16
	global_load_dwordx4 v[46:49], v[38:39], off
	global_load_dwordx4 v[42:45], v[38:39], off offset:16
	global_load_dwordx4 v[30:33], v[22:23], off
	global_load_dwordx4 v[26:29], v[22:23], off offset:16
	global_load_dwordx4 v[14:17], v[6:7], off
	global_load_dwordx4 v[10:13], v[6:7], off offset:16
	s_waitcnt vmcnt(6)
	v_pk_fma_f32 v[118:119], v[118:119], v[154:155], v[62:63]
	v_pk_fma_f32 v[120:121], v[120:121], v[152:153], v[64:65]
	v_pk_fma_f32 v[114:115], v[114:115], v[150:151], v[58:59]
	v_pk_fma_f32 v[116:117], v[116:117], v[148:149], v[60:61]
	global_store_dwordx4 v[50:51], v[118:121], off
	global_store_dwordx4 v[50:51], v[114:117], off offset:16
	s_waitcnt vmcnt(6)
	v_pk_fma_f32 v[102:103], v[102:103], v[154:155], v[46:47]
	v_pk_fma_f32 v[104:105], v[104:105], v[152:153], v[48:49]
	v_pk_fma_f32 v[98:99], v[98:99], v[150:151], v[42:43]
	v_pk_fma_f32 v[100:101], v[100:101], v[148:149], v[44:45]
	global_store_dwordx4 v[34:35], v[102:105], off
	global_store_dwordx4 v[34:35], v[98:101], off offset:16
	s_waitcnt vmcnt(6)
	v_pk_fma_f32 v[86:87], v[86:87], v[154:155], v[30:31]
	v_pk_fma_f32 v[88:89], v[88:89], v[152:153], v[32:33]
	v_pk_fma_f32 v[82:83], v[82:83], v[150:151], v[26:27]
	v_pk_fma_f32 v[84:85], v[84:85], v[148:149], v[28:29]
	global_store_dwordx4 v[18:19], v[86:89], off
	global_store_dwordx4 v[18:19], v[82:85], off offset:16
	s_waitcnt vmcnt(6)
	v_pk_fma_f32 v[70:71], v[70:71], v[154:155], v[14:15]
	v_pk_fma_f32 v[72:73], v[72:73], v[152:153], v[16:17]
	v_pk_fma_f32 v[66:67], v[66:67], v[150:151], v[10:11]
	v_pk_fma_f32 v[68:69], v[68:69], v[148:149], v[12:13]
	global_store_dwordx4 v[2:3], v[70:73], off
	global_store_dwordx4 v[2:3], v[66:69], off offset:16
	s_mov_b64 s[48:49], -1
	s_branch .Lkq_epi_end
.Lkq_epiQ4:
	s_barrier
	s_mov_b64 s[48:49], 0x80200
	v_lshl_add_u64 v[118:119], v[156:157], 0, s[48:49]
	v_lshl_add_u64 v[114:115], v[162:163], 0, s[48:49]
	s_mov_b64 s[48:49], 0x90200
	v_lshl_add_u64 v[102:103], v[156:157], 0, s[48:49]
	v_lshl_add_u64 v[98:99], v[162:163], 0, s[48:49]
	s_mov_b64 s[48:49], 0xa0200
	v_lshl_add_u64 v[86:87], v[156:157], 0, s[48:49]
	v_lshl_add_u64 v[82:83], v[162:163], 0, s[48:49]
	s_mov_b64 s[48:49], 0xb0200
	v_lshl_add_u64 v[70:71], v[156:157], 0, s[48:49]
	v_lshl_add_u64 v[66:67], v[162:163], 0, s[48:49]
	global_load_dwordx4 v[126:129], v[118:119], off
	global_load_dwordx4 v[122:125], v[118:119], off offset:16
	global_load_dwordx4 v[110:113], v[102:103], off
	global_load_dwordx4 v[106:109], v[102:103], off offset:16
	global_load_dwordx4 v[94:97], v[86:87], off
	global_load_dwordx4 v[90:93], v[86:87], off offset:16
	global_load_dwordx4 v[78:81], v[70:71], off
	global_load_dwordx4 v[74:77], v[70:71], off offset:16
	s_waitcnt vmcnt(6)
	v_pk_fma_f32 v[54:55], v[54:55], v[154:155], v[126:127]
	v_pk_fma_f32 v[56:57], v[56:57], v[152:153], v[128:129]
	v_pk_fma_f32 v[50:51], v[50:51], v[150:151], v[122:123]
	v_pk_fma_f32 v[52:53], v[52:53], v[148:149], v[124:125]
	global_store_dwordx4 v[114:115], v[54:57], off
	global_store_dwordx4 v[114:115], v[50:53], off offset:16
	s_waitcnt vmcnt(6)
	v_pk_fma_f32 v[38:39], v[38:39], v[154:155], v[110:111]
	v_pk_fma_f32 v[40:41], v[40:41], v[152:153], v[112:113]
	v_pk_fma_f32 v[34:35], v[34:35], v[150:151], v[106:107]
	v_pk_fma_f32 v[36:37], v[36:37], v[148:149], v[108:109]
	global_store_dwordx4 v[98:99], v[38:41], off
	global_store_dwordx4 v[98:99], v[34:37], off offset:16
	s_waitcnt vmcnt(6)
	v_pk_fma_f32 v[22:23], v[22:23], v[154:155], v[94:95]
	v_pk_fma_f32 v[24:25], v[24:25], v[152:153], v[96:97]
	v_pk_fma_f32 v[18:19], v[18:19], v[150:151], v[90:91]
	v_pk_fma_f32 v[20:21], v[20:21], v[148:149], v[92:93]
	global_store_dwordx4 v[82:83], v[22:25], off
	global_store_dwordx4 v[82:83], v[18:21], off offset:16
	s_waitcnt vmcnt(6)
	v_pk_fma_f32 v[6:7], v[6:7], v[154:155], v[78:79]
	v_pk_fma_f32 v[8:9], v[8:9], v[152:153], v[80:81]
	v_pk_fma_f32 v[2:3], v[2:3], v[150:151], v[74:75]
	v_pk_fma_f32 v[4:5], v[4:5], v[148:149], v[76:77]
	global_store_dwordx4 v[66:67], v[6:9], off
	global_store_dwordx4 v[66:67], v[2:5], off offset:16
	s_mov_b64 s[48:49], -1
	s_branch .Lkq_epi_end
